# full-line stores (8 rows x 128B, DPP exchange, permuted Bt rows) in all four norm-folded GEMM epilogues (phases 1,6,8,12)
# baseline (speedup 1.0000x reference)
; __device__ __forceinline__ u16 f2bf(float f) { unsigned u = __float_as_uint(f); u += 0x7FFFu + ((u >> 16) & 1u); return (u16)(u >> 16); }
; __device__ __forceinline__ void transpose_job(const float* W, int K, int N, int Npad, u16* dst, const float* gain, u16* tile) {
;     ...
;         for (int tt = 0; tt < 2; ++tt)
; #pragma unroll
;             for (int i = 0; i < 2; ++i) { const int k = (tid >> 4) + 32 * i, n4 = (tid & 15) * 4;
; #pragma unroll
;                 for (int j = 0; j < 4; ++j) tile[tt * 64 * 72 + (n4 + j) * 72 + k] = f2bf(v[tt][i][j] * gk[tt][i]); }
;         __syncthreads();
; #pragma unroll
;         for (int tt = 0; tt < 2; ++tt) { const int t = t0 + tt * gridDim.x;
;             if (t < ntiles) { const int k0 = (t % kt) * 64, n0 = (t / kt) * 64; const int n = tid >> 3, k8 = (tid & 7) * 8;
;                 const u32x4 w = *(const u32x4*)(tile + tt * 64 * 72 + n * 72 + k8); *(u32x4*)(dst + (size_t)(n0 + n) * K + k0 + k8) = w; } }
.LBB0_44:
	s_waitcnt vmcnt(0)
	v_mul_f32_e32 v2, v2, v29
	v_bfe_u32 v23, v2, 16, 1
	v_add3_u32 v2, v2, v23, s21
	ds_write_b16_d16_hi v28, v2
	v_mul_f32_e32 v2, v3, v29
	v_bfe_u32 v3, v2, 16, 1
	v_add3_u32 v2, v2, v3, s21
	ds_write_b16_d16_hi v28, v2 offset:144
	v_mul_f32_e32 v2, v4, v29
	v_bfe_u32 v3, v2, 16, 1
	v_add3_u32 v2, v2, v3, s21
	ds_write_b16_d16_hi v28, v2 offset:288
	v_mul_f32_e32 v2, v5, v29
	v_bfe_u32 v3, v2, 16, 1
	v_add3_u32 v2, v2, v3, s21
	ds_write_b16_d16_hi v28, v2 offset:432
	v_mul_f32_e32 v2, v6, v30
	v_bfe_u32 v3, v2, 16, 1
	v_add3_u32 v2, v2, v3, s21
	ds_write_b16_d16_hi v28, v2 offset:64
	v_mul_f32_e32 v2, v7, v30
	v_bfe_u32 v3, v2, 16, 1
	v_add3_u32 v2, v2, v3, s21
	ds_write_b16_d16_hi v28, v2 offset:208
	v_mul_f32_e32 v2, v8, v30
	v_bfe_u32 v3, v2, 16, 1
	v_add3_u32 v2, v2, v3, s21
	ds_write_b16_d16_hi v28, v2 offset:352
	v_mul_f32_e32 v2, v9, v30
	v_bfe_u32 v3, v2, 16, 1
	v_add3_u32 v2, v2, v3, s21
	ds_write_b16_d16_hi v28, v2 offset:496
	v_mul_f32_e32 v2, v10, v31
	v_bfe_u32 v3, v2, 16, 1
	v_add3_u32 v2, v2, v3, s21
	ds_write_b16_d16_hi v28, v2 offset:9216
	v_mul_f32_e32 v2, v11, v31
	v_bfe_u32 v3, v2, 16, 1
	v_add3_u32 v2, v2, v3, s21
	ds_write_b16_d16_hi v28, v2 offset:9360
	v_mul_f32_e32 v2, v12, v31
	v_bfe_u32 v3, v2, 16, 1
	v_add3_u32 v2, v2, v3, s21
	ds_write_b16_d16_hi v28, v2 offset:9504
	v_mul_f32_e32 v2, v13, v31
	v_bfe_u32 v3, v2, 16, 1
	v_add3_u32 v2, v2, v3, s21
	ds_write_b16_d16_hi v28, v2 offset:9648
	v_mul_f32_e32 v2, v14, v22
	v_bfe_u32 v3, v2, 16, 1
	v_add3_u32 v2, v2, v3, s21
	ds_write_b16_d16_hi v28, v2 offset:9280
	v_mul_f32_e32 v2, v15, v22
	v_bfe_u32 v3, v2, 16, 1
	v_add3_u32 v2, v2, v3, s21
	ds_write_b16_d16_hi v28, v2 offset:9424
	v_mul_f32_e32 v2, v16, v22
	v_bfe_u32 v3, v2, 16, 1
	v_add3_u32 v2, v2, v3, s21
	ds_write_b16_d16_hi v28, v2 offset:9568
	v_mul_f32_e32 v2, v17, v22
	v_bfe_u32 v3, v2, 16, 1
	v_add3_u32 v2, v2, v3, s21
	v_add_u32_e32 v6, s23, v24
	ds_write_b16_d16_hi v28, v2 offset:9712
	s_waitcnt lgkmcnt(0)
	s_barrier
	ds_read_b128 v[2:5], v25
	v_bfe_u32 v200, v6, 6, 2
	v_bfe_u32 v201, v6, 5, 1
	v_and_b32_e32 v6, 0xffffff1f, v6
	v_lshl_or_b32 v6, v200, 5, v6
	v_lshl_or_b32 v6, v201, 7, v6
	v_ashrrev_i32_e32 v7, 31, v6
	v_lshlrev_b64 v[6:7], 11, v[6:7]
	v_lshl_add_u64 v[6:7], s[74:75], 0, v[6:7]
	s_ashr_i32 s9, s8, 31
	v_lshl_add_u64 v[6:7], s[8:9], 1, v[6:7]
	v_lshl_add_u64 v[6:7], v[6:7], 0, v[20:21]
	s_and_b64 vcc, exec, s[2:3]
	s_waitcnt lgkmcnt(0)
	global_store_dwordx4 v[6:7], v[2:5], off
	s_cbranch_vccnz .LBB0_19
	s_ashr_i32 s2, s24, 31
	s_lshr_b32 s2, s2, 28
	s_add_i32 s3, s24, s2
	s_and_b32 s2, s3, 0x3fffff0
	s_lshl_b32 s3, s3, 2
	s_andn2_b32 s3, s3, 63
	v_add_u32_e32 v6, s3, v24
	s_sub_i32 s2, s24, s2
	ds_read_b128 v[2:5], v25 offset:9216
	v_bfe_u32 v200, v6, 6, 2
	v_bfe_u32 v201, v6, 5, 1
	v_and_b32_e32 v6, 0xffffff1f, v6
	v_lshl_or_b32 v6, v200, 5, v6
	v_lshl_or_b32 v6, v201, 7, v6
	v_ashrrev_i32_e32 v7, 31, v6
	s_lshl_b32 s2, s2, 6
	v_lshlrev_b64 v[6:7], 11, v[6:7]
	v_lshl_add_u64 v[6:7], s[74:75], 0, v[6:7]
	s_ashr_i32 s3, s2, 31
	v_lshl_add_u64 v[6:7], s[2:3], 1, v[6:7]
	v_lshl_add_u64 v[6:7], v[6:7], 0, v[20:21]
	s_waitcnt lgkmcnt(0)
	global_store_dwordx4 v[6:7], v[2:5], off
	s_branch .LBB0_19

; __device__ __forceinline__ u16 f2bf(float f) { unsigned u = __float_as_uint(f); u += 0x7FFFu + ((u >> 16) & 1u); return (u16)(u >> 16); }
; __device__ __forceinline__ void transpose_job(const float* W, int K, int N, int Npad, u16* dst, const float* gain, u16* tile) {
;     ...
;         for (int tt = 0; tt < 2; ++tt) { const int t = t0 + tt * gridDim.x; const bool ok = t < ntiles; const int k0 = ok ? (t % kt) * 64 : 0, n0 = ok ? (t / kt) * 64 : 0;
; #pragma unroll
;             for (int i = 0; i < 2; ++i) { const int k = (tid >> 4) + 32 * i, n = n0 + (tid & 15) * 4;
;                 v[tt][i] = (f32x4){0.f, 0.f, 0.f, 0.f}; if (ok && n < N) v[tt][i] = *(const f32x4*)(W + (size_t)(k0 + k) * N + n);
;                 gk[tt][i] = gain ? gain[k0 + k] : 1.0f; } }
; #pragma unroll
;         for (int tt = 0; tt < 2; ++tt)
; #pragma unroll
;             for (int i = 0; i < 2; ++i) { const int k = (tid >> 4) + 32 * i, n4 = (tid & 15) * 4;
; #pragma unroll
;                 for (int j = 0; j < 4; ++j) tile[tt * 64 * 72 + (n4 + j) * 72 + k] = f2bf(v[tt][i][j] * gk[tt][i]); }
;         __syncthreads();
; #pragma unroll
;         for (int tt = 0; tt < 2; ++tt) { const int t = t0 + tt * gridDim.x;
;             if (t < ntiles) { const int k0 = (t % kt) * 64, n0 = (t / kt) * 64; const int n = tid >> 3, k8 = (tid & 7) * 8;
;                 const u32x4 w = *(const u32x4*)(tile + tt * 64 * 72 + n * 72 + k8); *(u32x4*)(dst + (size_t)(n0 + n) * K + k0 + k8) = w; } }
.LBB0_155:
	s_or_b64 exec, exec, s[12:13]
	v_ashrrev_i32_e32 v25, 31, v24
	v_lshl_add_u64 v[22:23], v[24:25], 2, s[8:9]
	global_load_dword v22, v[22:23], off
	s_waitcnt vmcnt(3)
	v_mul_f32_e32 v23, v2, v30
	v_mul_f32_e32 v4, v4, v30
	v_mul_f32_e32 v5, v5, v30
	v_mul_f32_e32 v24, v3, v30
	s_waitcnt vmcnt(2)
	v_mul_f32_e32 v6, v6, v31
	v_mul_f32_e32 v7, v7, v31
	v_mul_f32_e32 v8, v8, v31
	v_mul_f32_e32 v9, v9, v31
	s_waitcnt vmcnt(1)
	v_mul_f32_e32 v14, v14, v32
	v_mul_f32_e32 v15, v15, v32
	v_mul_f32_e32 v16, v16, v32
	v_mul_f32_e32 v17, v17, v32
	v_add_u32_e32 v2, s21, v19
	v_bfe_u32 v25, v23, 16, 1
	v_bfe_u32 v31, v4, 16, 1
	v_bfe_u32 v32, v5, 16, 1
	v_bfe_u32 v30, v24, 16, 1
	v_bfe_u32 v33, v6, 16, 1
	v_bfe_u32 v34, v7, 16, 1
	v_bfe_u32 v35, v8, 16, 1
	v_bfe_u32 v36, v9, 16, 1
	v_bfe_u32 v37, v14, 16, 1
	v_bfe_u32 v38, v15, 16, 1
	v_bfe_u32 v39, v16, 16, 1
	v_bfe_u32 v40, v17, 16, 1
	v_bfe_u32 v200, v2, 6, 2
	v_bfe_u32 v201, v2, 5, 1
	v_and_b32_e32 v2, 0xffffff1f, v2
	v_lshl_or_b32 v2, v200, 5, v2
	v_lshl_or_b32 v2, v201, 7, v2
	v_ashrrev_i32_e32 v3, 31, v2
	v_add3_u32 v23, v23, v25, s19
	v_add3_u32 v4, v4, v31, s19
	v_add3_u32 v5, v5, v32, s19
	v_add3_u32 v24, v24, v30, s19
	v_add3_u32 v25, v6, v33, s19
	v_add3_u32 v30, v7, v34, s19
	v_add3_u32 v8, v8, v35, s19
	v_add3_u32 v9, v9, v36, s19
	v_add3_u32 v14, v14, v37, s19
	v_add3_u32 v15, v15, v38, s19
	v_add3_u32 v16, v16, v39, s19
	v_add3_u32 v17, v17, v40, s19
	v_lshlrev_b64 v[6:7], 11, v[2:3]
	ds_write_b16_d16_hi v29, v23
	ds_write_b16_d16_hi v29, v24 offset:144
	ds_write_b16_d16_hi v29, v4 offset:288
	ds_write_b16_d16_hi v29, v5 offset:432
	ds_write_b16_d16_hi v29, v25 offset:64
	ds_write_b16_d16_hi v29, v30 offset:208
	ds_write_b16_d16_hi v29, v8 offset:352
	ds_write_b16_d16_hi v29, v9 offset:496
	ds_write_b16_d16_hi v29, v14 offset:9216
	ds_write_b16_d16_hi v29, v15 offset:9360
	ds_write_b16_d16_hi v29, v16 offset:9504
	ds_write_b16_d16_hi v29, v17 offset:9648
	s_sub_i32 s10, 0, s23
	s_add_i32 s10, s15, s10
	v_lshl_add_u64 v[6:7], s[2:3], 0, v[6:7]
	s_ashr_i32 s11, s10, 31
	v_lshl_add_u64 v[6:7], s[10:11], 1, v[6:7]
	v_lshl_add_u64 v[6:7], v[6:7], 0, v[20:21]
	s_and_b64 vcc, exec, s[0:1]
	s_waitcnt vmcnt(0)
	v_mul_f32_e32 v2, v10, v22
	v_mul_f32_e32 v3, v11, v22
	v_mul_f32_e32 v4, v12, v22
	v_mul_f32_e32 v5, v13, v22
	v_bfe_u32 v8, v2, 16, 1
	v_bfe_u32 v9, v3, 16, 1
	v_bfe_u32 v10, v4, 16, 1
	v_bfe_u32 v11, v5, 16, 1
	v_add3_u32 v2, v2, v8, s19
	v_add3_u32 v3, v3, v9, s19
	v_add3_u32 v4, v4, v10, s19
	v_add3_u32 v5, v5, v11, s19
	ds_write_b16_d16_hi v29, v2 offset:9280
	ds_write_b16_d16_hi v29, v3 offset:9424
	ds_write_b16_d16_hi v29, v4 offset:9568
	ds_write_b16_d16_hi v29, v5 offset:9712
	s_waitcnt lgkmcnt(0)
	s_barrier
	ds_read_b128 v[2:5], v26
	s_waitcnt lgkmcnt(0)
	global_store_dwordx4 v[6:7], v[2:5], off
	s_cbranch_vccnz .LBB0_142
	s_ashr_i32 s0, s22, 31
	s_lshr_b32 s0, s0, 28
	s_add_i32 s1, s22, s0
	s_and_b32 s0, s1, 0x3fffff0
	s_lshl_b32 s1, s1, 2
	s_andn2_b32 s1, s1, 63
	v_add_u32_e32 v6, s1, v19
	s_sub_i32 s0, s22, s0
	ds_read_b128 v[2:5], v26 offset:9216
	v_bfe_u32 v200, v6, 6, 2
	v_bfe_u32 v201, v6, 5, 1
	v_and_b32_e32 v6, 0xffffff1f, v6
	v_lshl_or_b32 v6, v200, 5, v6
	v_lshl_or_b32 v6, v201, 7, v6
	v_ashrrev_i32_e32 v7, 31, v6
	s_lshl_b32 s0, s0, 6
	v_lshlrev_b64 v[6:7], 11, v[6:7]
	v_lshl_add_u64 v[6:7], s[2:3], 0, v[6:7]
	s_ashr_i32 s1, s0, 31
	v_lshl_add_u64 v[6:7], s[0:1], 1, v[6:7]
	v_lshl_add_u64 v[6:7], v[6:7], 0, v[20:21]
	s_waitcnt lgkmcnt(0)
	global_store_dwordx4 v[6:7], v[2:5], off
	s_branch .LBB0_142

; #define PG8_STAGE(bufoff, gbase, voff) do { _Pragma("unroll") for (int _i = 0; _i < 2; ++_i) \
;         __builtin_amdgcn_global_load_lds((const unsigned*)((const char*)(gbase) + (voff)[_i]), (LAS unsigned*)(lds + (bufoff) + ldsw + _i * 8192), 16, 0, 0); } while (0)
; #define PG8_LDA(dst, b, h) do { _Pragma("unroll") for (int m = 0; m < 4; ++m) _Pragma("unroll") for (int k = 0; k < 2; ++k) dst[m][k] = *(const LAS bf16x8*)(lds + PG8_SA(b, h) + aoff + m * 2048 + k * 1024); } while (0)
; #define PG8_LDB(dst, b, h) do { _Pragma("unroll") for (int n = 0; n < 2; ++n) _Pragma("unroll") for (int k = 0; k < 2; ++k) dst[n][k] = *(const LAS bf16x8*)(lds + PG8_SB(b, h) + boff + n * 2048 + k * 1024); } while (0)
; #define PG8_MMA(ai, bj, At, Bt) do { __builtin_amdgcn_s_setprio(1); _Pragma("unroll") for (int m = 0; m < 4; ++m) _Pragma("unroll") for (int n = 0; n < 2; ++n) _Pragma("unroll") for (int k = 0; k < 2; ++k) \
;         acc[ai][bj][m][n] = __builtin_amdgcn_mfma_f32_16x16x32_bf16(Bt[n][k], At[m][k], acc[ai][bj][m][n], 0, 0, 0); __builtin_amdgcn_s_setprio(0); } while (0)
; #define PG8_WAIT_V(n) asm volatile("s_waitcnt vmcnt(" #n ")" ::: "memory")
; #define PG8_WAIT_L(n) asm volatile("s_waitcnt lgkmcnt(" #n ")" ::: "memory")
; #define PG8_BAR __builtin_amdgcn_s_barrier()
; #define PG8_SCHED __builtin_amdgcn_sched_barrier(0)
; template <class Epi>
; __device__ __forceinline__ void gemm_phase(LAS unsigned char* lds, const Gemm g, const StaticOrder& S, const Epi& E) {
;     ...
;             PG8_LDB(B0, 0, 0); PG8_SCHED; PG8_LDA(At, 0, 0); PG8_STAGE(PG8_SA(1, 1), a1 + hstepA, voffA);
;             PG8_WAIT_L(8); PG8_BAR; PG8_WAIT_L(0); PG8_MMA(0, 0, At, B0); PG8_BAR; PG8_SCHED;
;             PG8_LDB(B1, 0, 1); PG8_STAGE(PG8_SB(0, 0), b2, voffB);
;             PG8_BAR; PG8_WAIT_L(0); PG8_MMA(0, 1, At, B1); PG8_BAR;
;             PG8_LDA(At, 0, 1); PG8_STAGE(PG8_SA(0, 0), a2, voffA);
;             PG8_BAR; PG8_WAIT_L(0); PG8_MMA(1, 0, At, B0); PG8_BAR; PG8_SCHED;
;             PG8_STAGE(PG8_SB(0, 1), b2 + hstepB, voffB);
;             PG8_WAIT_V(6); PG8_BAR; PG8_MMA(1, 1, At, B1); PG8_BAR;
.LBB0_205:
	ds_read_b128 v[146:149], v170
	ds_read_b128 v[154:157], v170 offset:1024
	ds_read_b128 v[158:161], v170 offset:2048
	ds_read_b128 v[162:165], v170 offset:3072
	s_add_u32 s22, s20, 0xfffc0080
	s_addc_u32 s23, s21, -1
	s_cmp_eq_u32 s47, 12
	s_cselect_b32 s25, s13, s23
	s_cselect_b32 s24, s19, s22
	s_cselect_b32 s23, s11, s46
	s_cselect_b32 s22, s44, s45
	v_lshl_add_u64 v[150:151], s[20:21], 0, v[138:139]
	s_add_i32 m0, s30, 0xc000
	s_waitcnt vmcnt(0)
	ds_read_b128 v[174:177], v171
	ds_read_b128 v[178:181], v171 offset:1024
	ds_read_b128 v[182:185], v171 offset:2048
	ds_read_b128 v[186:189], v171 offset:3072
	ds_read_b128 v[190:193], v171 offset:4096
	ds_read_b128 v[194:197], v171 offset:5120
	ds_read_b128 v[198:201], v171 offset:6144
	ds_read_b128 v[202:205], v171 offset:7168
	global_load_lds_dwordx4 v[150:151], off
	v_lshl_add_u64 v[150:151], s[20:21], 0, v[140:141]
	s_add_i32 m0, s30, 0xe000
	s_nop 0
	global_load_lds_dwordx4 v[150:151], off
	s_waitcnt lgkmcnt(8)
	s_barrier
	s_waitcnt lgkmcnt(0)
	s_setprio 1
	s_waitcnt lgkmcnt(0)
	v_mfma_f32_16x16x32_bf16 v[76:79], v[146:149], v[174:177], v[76:79]
	v_mfma_f32_16x16x32_bf16 v[64:67], v[158:161], v[174:177], v[64:67]
	v_mfma_f32_16x16x32_bf16 v[60:63], v[146:149], v[182:185], v[60:63]
	v_mfma_f32_16x16x32_bf16 v[56:59], v[158:161], v[182:185], v[56:59]
	v_mfma_f32_16x16x32_bf16 v[48:51], v[146:149], v[190:193], v[48:51]
	v_mfma_f32_16x16x32_bf16 v[40:43], v[158:161], v[190:193], v[40:43]
	v_mfma_f32_16x16x32_bf16 v[36:39], v[146:149], v[198:201], v[36:39]
	v_mfma_f32_16x16x32_bf16 v[32:35], v[158:161], v[198:201], v[32:35]
	v_mfma_f32_16x16x32_bf16 v[76:79], v[154:157], v[178:181], v[76:79]
	v_mfma_f32_16x16x32_bf16 v[64:67], v[162:165], v[178:181], v[64:67]
	v_mfma_f32_16x16x32_bf16 v[60:63], v[154:157], v[186:189], v[60:63]
	v_mfma_f32_16x16x32_bf16 v[56:59], v[162:165], v[186:189], v[56:59]
	v_mfma_f32_16x16x32_bf16 v[48:51], v[154:157], v[194:197], v[48:51]
	v_mfma_f32_16x16x32_bf16 v[40:43], v[162:165], v[194:197], v[40:43]
	v_mfma_f32_16x16x32_bf16 v[36:39], v[154:157], v[202:205], v[36:39]
	v_mfma_f32_16x16x32_bf16 v[32:35], v[162:165], v[202:205], v[32:35]
	s_setprio 0
	s_barrier
	s_add_i32 s48, s39, s27
	v_lshl_add_u64 v[150:151], s[22:23], 0, v[132:133]
	s_mov_b32 m0, s48
	ds_read_b128 v[206:209], v172
	ds_read_b128 v[210:213], v172 offset:1024
	ds_read_b128 v[214:217], v172 offset:2048
	ds_read_b128 v[218:221], v172 offset:3072
	global_load_lds_dwordx4 v[150:151], off
	v_lshl_add_u64 v[166:167], s[22:23], 0, v[128:129]
	s_add_i32 m0, s48, 0x2000
	s_nop 0
	global_load_lds_dwordx4 v[166:167], off
	s_barrier
	s_waitcnt lgkmcnt(0)
	s_setprio 1
	s_waitcnt lgkmcnt(0)
	v_mfma_f32_16x16x32_bf16 v[124:127], v[206:209], v[174:177], v[124:127]
	v_mfma_f32_16x16x32_bf16 v[120:123], v[214:217], v[174:177], v[120:123]
	v_mfma_f32_16x16x32_bf16 v[116:119], v[206:209], v[182:185], v[116:119]
	v_mfma_f32_16x16x32_bf16 v[112:115], v[214:217], v[182:185], v[112:115]
	v_mfma_f32_16x16x32_bf16 v[108:111], v[206:209], v[190:193], v[108:111]
	v_mfma_f32_16x16x32_bf16 v[104:107], v[214:217], v[190:193], v[104:107]
	v_mfma_f32_16x16x32_bf16 v[100:103], v[206:209], v[198:201], v[100:103]
	v_mfma_f32_16x16x32_bf16 v[96:99], v[214:217], v[198:201], v[96:99]
	v_mfma_f32_16x16x32_bf16 v[124:127], v[210:213], v[178:181], v[124:127]
	v_mfma_f32_16x16x32_bf16 v[120:123], v[218:221], v[178:181], v[120:123]
	v_mfma_f32_16x16x32_bf16 v[116:119], v[210:213], v[186:189], v[116:119]
	v_mfma_f32_16x16x32_bf16 v[112:115], v[218:221], v[186:189], v[112:115]
	v_mfma_f32_16x16x32_bf16 v[108:111], v[210:213], v[194:197], v[108:111]
	v_mfma_f32_16x16x32_bf16 v[104:107], v[218:221], v[194:197], v[104:107]
	v_mfma_f32_16x16x32_bf16 v[100:103], v[210:213], v[202:205], v[100:103]
	v_mfma_f32_16x16x32_bf16 v[96:99], v[218:221], v[202:205], v[96:99]
	s_setprio 0
	s_mov_b32 m0, s30
	v_lshl_add_u64 v[222:223], s[24:25], 0, v[134:135]
	s_barrier
	ds_read_b128 v[174:177], v171 offset:16384
	ds_read_b128 v[178:181], v171 offset:17408
	ds_read_b128 v[182:185], v171 offset:18432
	ds_read_b128 v[186:189], v171 offset:19456
	ds_read_b128 v[190:193], v171 offset:20480
	ds_read_b128 v[194:197], v171 offset:21504
	ds_read_b128 v[198:201], v171 offset:22528
	ds_read_b128 v[202:205], v171 offset:23552
	global_load_lds_dwordx4 v[222:223], off
	v_lshl_add_u64 v[224:225], s[24:25], 0, v[130:131]
	s_mov_b32 m0, s31
	s_nop 0
	global_load_lds_dwordx4 v[224:225], off
	s_barrier
	s_waitcnt lgkmcnt(0)
	s_setprio 1
	s_waitcnt lgkmcnt(0)
	v_mfma_f32_16x16x32_bf16 v[28:31], v[146:149], v[174:177], v[28:31]
	v_mfma_f32_16x16x32_bf16 v[24:27], v[158:161], v[174:177], v[24:27]
	v_mfma_f32_16x16x32_bf16 v[20:23], v[146:149], v[182:185], v[20:23]
	v_mfma_f32_16x16x32_bf16 v[16:19], v[158:161], v[182:185], v[16:19]
	v_mfma_f32_16x16x32_bf16 v[12:15], v[146:149], v[190:193], v[12:15]
	v_mfma_f32_16x16x32_bf16 v[8:11], v[158:161], v[190:193], v[8:11]
	v_mfma_f32_16x16x32_bf16 v[4:7], v[146:149], v[198:201], v[4:7]
	v_mfma_f32_16x16x32_bf16 v[0:3], v[158:161], v[198:201], v[0:3]
	v_mfma_f32_16x16x32_bf16 v[28:31], v[154:157], v[178:181], v[28:31]
	v_mfma_f32_16x16x32_bf16 v[24:27], v[162:165], v[178:181], v[24:27]
	v_mfma_f32_16x16x32_bf16 v[20:23], v[154:157], v[186:189], v[20:23]
	v_mfma_f32_16x16x32_bf16 v[16:19], v[162:165], v[186:189], v[16:19]
	v_mfma_f32_16x16x32_bf16 v[12:15], v[154:157], v[194:197], v[12:15]
	v_mfma_f32_16x16x32_bf16 v[8:11], v[162:165], v[194:197], v[8:11]
	v_mfma_f32_16x16x32_bf16 v[4:7], v[154:157], v[202:205], v[4:7]
	v_mfma_f32_16x16x32_bf16 v[0:3], v[162:165], v[202:205], v[0:3]
	s_setprio 0
	s_barrier
; #define PG8_STAGE(bufoff, gbase, voff) do { _Pragma("unroll") for (int _i = 0; _i < 2; ++_i) \
;         __builtin_amdgcn_global_load_lds((const unsigned*)((const char*)(gbase) + (voff)[_i]), (LAS unsigned*)(lds + (bufoff) + ldsw + _i * 8192), 16, 0, 0); } while (0)
; #define PG8_LDA(dst, b, h) do { _Pragma("unroll") for (int m = 0; m < 4; ++m) _Pragma("unroll") for (int k = 0; k < 2; ++k) dst[m][k] = *(const LAS bf16x8*)(lds + PG8_SA(b, h) + aoff + m * 2048 + k * 1024); } while (0)
; #define PG8_LDB(dst, b, h) do { _Pragma("unroll") for (int n = 0; n < 2; ++n) _Pragma("unroll") for (int k = 0; k < 2; ++k) dst[n][k] = *(const LAS bf16x8*)(lds + PG8_SB(b, h) + boff + n * 2048 + k * 1024); } while (0)
; #define PG8_MMA(ai, bj, At, Bt) do { __builtin_amdgcn_s_setprio(1); _Pragma("unroll") for (int m = 0; m < 4; ++m) _Pragma("unroll") for (int n = 0; n < 2; ++n) _Pragma("unroll") for (int k = 0; k < 2; ++k) \
;         acc[ai][bj][m][n] = __builtin_amdgcn_mfma_f32_16x16x32_bf16(Bt[n][k], At[m][k], acc[ai][bj][m][n], 0, 0, 0); __builtin_amdgcn_s_setprio(0); } while (0)
; #define PG8_WAIT_V(n) asm volatile("s_waitcnt vmcnt(" #n ")" ::: "memory")
; #define PG8_WAIT_L(n) asm volatile("s_waitcnt lgkmcnt(" #n ")" ::: "memory")
; #define PG8_BAR __builtin_amdgcn_s_barrier()
; #define PG8_SCHED __builtin_amdgcn_sched_barrier(0)
; template <class Epi>
; __device__ __forceinline__ void gemm_phase(LAS unsigned char* lds, const Gemm g, const StaticOrder& S, const Epi& E) {
;     ...
;             PG8_WAIT_V(6); PG8_BAR; PG8_MMA(1, 1, At, B1); PG8_BAR;
;             PG8_LDB(B0, 1, 0); PG8_SCHED; PG8_LDA(At, 1, 0); PG8_STAGE(PG8_SA(0, 1), a2 + hstepA, voffA);
;             PG8_WAIT_L(8); PG8_BAR; PG8_WAIT_L(0); PG8_MMA(0, 0, At, B0); PG8_BAR; PG8_SCHED;
;             PG8_LDB(B1, 1, 1); PG8_STAGE(PG8_SB(1, 0), b3, voffB);
;             PG8_BAR; PG8_WAIT_L(0); PG8_MMA(0, 1, At, B1); PG8_BAR;
;             PG8_LDA(At, 1, 1); PG8_STAGE(PG8_SA(1, 0), a3, voffA);
;             PG8_BAR; PG8_WAIT_L(0); PG8_MMA(1, 0, At, B0); PG8_BAR; PG8_SCHED;
	s_add_u32 s48, s22, 0x40000
	s_addc_u32 s49, s23, 0
	s_add_i32 s50, s40, s27
	v_lshl_add_u64 v[146:147], s[48:49], 0, v[132:133]
	s_mov_b32 m0, s50
	s_nop 0
	global_load_lds_dwordx4 v[146:147], off
	v_lshl_add_u64 v[146:147], s[48:49], 0, v[128:129]
	s_add_i32 m0, s50, 0x2000
	s_nop 0
	global_load_lds_dwordx4 v[146:147], off
	s_waitcnt vmcnt(6)
	s_barrier
	s_setprio 1
	v_mfma_f32_16x16x32_bf16 v[92:95], v[206:209], v[174:177], v[92:95]
	v_mfma_f32_16x16x32_bf16 v[88:91], v[214:217], v[174:177], v[88:91]
	v_mfma_f32_16x16x32_bf16 v[84:87], v[206:209], v[182:185], v[84:87]
	v_mfma_f32_16x16x32_bf16 v[80:83], v[214:217], v[182:185], v[80:83]
	v_mfma_f32_16x16x32_bf16 v[72:75], v[206:209], v[190:193], v[72:75]
	v_mfma_f32_16x16x32_bf16 v[68:71], v[214:217], v[190:193], v[68:71]
	v_mfma_f32_16x16x32_bf16 v[52:55], v[206:209], v[198:201], v[52:55]
	v_mfma_f32_16x16x32_bf16 v[44:47], v[214:217], v[198:201], v[44:47]
	v_mfma_f32_16x16x32_bf16 v[92:95], v[210:213], v[178:181], v[92:95]
	v_mfma_f32_16x16x32_bf16 v[88:91], v[218:221], v[178:181], v[88:91]
	v_mfma_f32_16x16x32_bf16 v[84:87], v[210:213], v[186:189], v[84:87]
	v_mfma_f32_16x16x32_bf16 v[80:83], v[218:221], v[186:189], v[80:83]
	v_mfma_f32_16x16x32_bf16 v[72:75], v[210:213], v[194:197], v[72:75]
	v_mfma_f32_16x16x32_bf16 v[68:71], v[218:221], v[194:197], v[68:71]
	v_mfma_f32_16x16x32_bf16 v[52:55], v[210:213], v[202:205], v[52:55]
	v_mfma_f32_16x16x32_bf16 v[44:47], v[218:221], v[202:205], v[44:47]
	s_setprio 0
	s_add_i32 s48, 0, 0x18000
	v_add_u32_e32 v162, s48, v168
	s_barrier
	ds_read_b128 v[146:149], v162
	ds_read_b128 v[154:157], v162 offset:1024
	ds_read_b128 v[158:161], v162 offset:2048
	ds_read_b128 v[162:165], v162 offset:3072
	s_add_u32 s24, s24, 0x40000
	s_addc_u32 s25, s25, 0
	s_mov_b32 m0, s33
	v_lshl_add_u64 v[206:207], s[24:25], 0, v[134:135]
	ds_read_b128 v[174:177], v171 offset:32768
	ds_read_b128 v[178:181], v171 offset:33792
	ds_read_b128 v[182:185], v171 offset:34816
	ds_read_b128 v[186:189], v171 offset:35840
	ds_read_b128 v[190:193], v171 offset:36864
	ds_read_b128 v[194:197], v171 offset:37888
	ds_read_b128 v[198:201], v171 offset:38912
	ds_read_b128 v[202:205], v171 offset:39936
	global_load_lds_dwordx4 v[206:207], off
	v_lshl_add_u64 v[206:207], s[24:25], 0, v[130:131]
	s_mov_b32 m0, s34
	s_nop 0
	global_load_lds_dwordx4 v[206:207], off
	s_waitcnt lgkmcnt(8)
	s_barrier
	s_waitcnt lgkmcnt(0)
	s_setprio 1
	s_waitcnt lgkmcnt(0)
	v_mfma_f32_16x16x32_bf16 v[76:79], v[146:149], v[174:177], v[76:79]
	v_mfma_f32_16x16x32_bf16 v[64:67], v[158:161], v[174:177], v[64:67]
	v_mfma_f32_16x16x32_bf16 v[60:63], v[146:149], v[182:185], v[60:63]
	v_mfma_f32_16x16x32_bf16 v[56:59], v[158:161], v[182:185], v[56:59]
	v_mfma_f32_16x16x32_bf16 v[48:51], v[146:149], v[190:193], v[48:51]
	v_mfma_f32_16x16x32_bf16 v[40:43], v[158:161], v[190:193], v[40:43]
	v_mfma_f32_16x16x32_bf16 v[36:39], v[146:149], v[198:201], v[36:39]
	v_mfma_f32_16x16x32_bf16 v[32:35], v[158:161], v[198:201], v[32:35]
	v_mfma_f32_16x16x32_bf16 v[76:79], v[154:157], v[178:181], v[76:79]
	v_mfma_f32_16x16x32_bf16 v[64:67], v[162:165], v[178:181], v[64:67]
	v_mfma_f32_16x16x32_bf16 v[60:63], v[154:157], v[186:189], v[60:63]
	v_mfma_f32_16x16x32_bf16 v[56:59], v[162:165], v[186:189], v[56:59]
	v_mfma_f32_16x16x32_bf16 v[48:51], v[154:157], v[194:197], v[48:51]
	v_mfma_f32_16x16x32_bf16 v[40:43], v[162:165], v[194:197], v[40:43]
	v_mfma_f32_16x16x32_bf16 v[36:39], v[154:157], v[202:205], v[36:39]
	v_mfma_f32_16x16x32_bf16 v[32:35], v[162:165], v[202:205], v[32:35]
	s_setprio 0
	s_barrier
	s_add_i32 s24, 0, 0x1c000
	s_add_i32 s25, s48, s27
	v_add_u32_e32 v218, s24, v168
	v_lshl_add_u64 v[150:151], v[150:151], 0, s[6:7]
	s_mov_b32 m0, s25
	ds_read_b128 v[206:209], v218
	ds_read_b128 v[210:213], v218 offset:1024
	ds_read_b128 v[214:217], v218 offset:2048
	ds_read_b128 v[218:221], v218 offset:3072
	global_load_lds_dwordx4 v[150:151], off
	v_lshl_add_u64 v[150:151], v[166:167], 0, s[6:7]
	s_add_i32 m0, s25, 0x2000
	s_nop 0
	global_load_lds_dwordx4 v[150:151], off
	s_barrier
	s_waitcnt lgkmcnt(0)
	s_setprio 1
	s_waitcnt lgkmcnt(0)
	v_mfma_f32_16x16x32_bf16 v[124:127], v[206:209], v[174:177], v[124:127]
	v_mfma_f32_16x16x32_bf16 v[120:123], v[214:217], v[174:177], v[120:123]
	v_mfma_f32_16x16x32_bf16 v[116:119], v[206:209], v[182:185], v[116:119]
	v_mfma_f32_16x16x32_bf16 v[112:115], v[214:217], v[182:185], v[112:115]
	v_mfma_f32_16x16x32_bf16 v[108:111], v[206:209], v[190:193], v[108:111]
	v_mfma_f32_16x16x32_bf16 v[104:107], v[214:217], v[190:193], v[104:107]
	v_mfma_f32_16x16x32_bf16 v[100:103], v[206:209], v[198:201], v[100:103]
	v_mfma_f32_16x16x32_bf16 v[96:99], v[214:217], v[198:201], v[96:99]
	v_mfma_f32_16x16x32_bf16 v[124:127], v[210:213], v[178:181], v[124:127]
	v_mfma_f32_16x16x32_bf16 v[120:123], v[218:221], v[178:181], v[120:123]
	v_mfma_f32_16x16x32_bf16 v[116:119], v[210:213], v[186:189], v[116:119]
	v_mfma_f32_16x16x32_bf16 v[112:115], v[218:221], v[186:189], v[112:115]
	v_mfma_f32_16x16x32_bf16 v[108:111], v[210:213], v[194:197], v[108:111]
	v_mfma_f32_16x16x32_bf16 v[104:107], v[218:221], v[194:197], v[104:107]
	v_mfma_f32_16x16x32_bf16 v[100:103], v[210:213], v[202:205], v[100:103]
	v_mfma_f32_16x16x32_bf16 v[96:99], v[218:221], v[202:205], v[96:99]
	s_setprio 0
	s_mov_b32 m0, s36
	v_lshl_add_u64 v[150:151], v[222:223], 0, s[6:7]
	s_barrier
	ds_read_b128 v[174:177], v171 offset:49152
	ds_read_b128 v[178:181], v171 offset:50176
	ds_read_b128 v[182:185], v171 offset:51200
	ds_read_b128 v[186:189], v171 offset:52224
	ds_read_b128 v[190:193], v171 offset:53248
	ds_read_b128 v[194:197], v171 offset:54272
	ds_read_b128 v[198:201], v171 offset:55296
	ds_read_b128 v[202:205], v171 offset:56320
	global_load_lds_dwordx4 v[150:151], off
	v_lshl_add_u64 v[150:151], v[224:225], 0, s[6:7]
	s_mov_b32 m0, s37
	s_nop 0
	global_load_lds_dwordx4 v[150:151], off
	s_barrier
; __device__ __forceinline__ unsigned pk2(float lo, float hi) { const f32x2 v = (f32x2){lo, hi}; const bf16x2_t b = __builtin_convertvector(v, bf16x2_t); return __builtin_bit_cast(unsigned, b); }
; #define PG8_STAGE(bufoff, gbase, voff) do { _Pragma("unroll") for (int _i = 0; _i < 2; ++_i) \
;         __builtin_amdgcn_global_load_lds((const unsigned*)((const char*)(gbase) + (voff)[_i]), (LAS unsigned*)(lds + (bufoff) + ldsw + _i * 8192), 16, 0, 0); } while (0)
; #define PG8_MMA(ai, bj, At, Bt) do { __builtin_amdgcn_s_setprio(1); _Pragma("unroll") for (int m = 0; m < 4; ++m) _Pragma("unroll") for (int n = 0; n < 2; ++n) _Pragma("unroll") for (int k = 0; k < 2; ++k) \
;         acc[ai][bj][m][n] = __builtin_amdgcn_mfma_f32_16x16x32_bf16(Bt[n][k], At[m][k], acc[ai][bj][m][n], 0, 0, 0); __builtin_amdgcn_s_setprio(0); } while (0)
; #define PG8_WAIT_V(n) asm volatile("s_waitcnt vmcnt(" #n ")" ::: "memory")
; #define PG8_WAIT_L(n) asm volatile("s_waitcnt lgkmcnt(" #n ")" ::: "memory")
;     __device__ __forceinline__ void operator()(const f32x4 (&acc)[2][2][4][2], const Unit& u, int wr, int wc, int fr, int fq, const float (&)[8]) const {
;     ...
;         const int col0 = u.pn * BM + wc * 32 + 8 * fq;
; #pragma unroll
;         for (int ai = 0; ai < 2; ++ai)
; #pragma unroll
;             for (int m = 0; m < 4; ++m) { const int row = row0 + ai * HALF + m * 16; const float rs = rsqrtf(ep[ai * 4 + m] * (1.0f / 1024.0f) + EPS);
;                 u16* rowp = O + (size_t)row * ldc + col0;
; #pragma unroll
;                 for (int bj = 0; bj < 2; ++bj) { f32x4 v0 = acc[ai][bj][m][0] * rs, v1 = acc[ai][bj][m][1] * rs;
;                     if (ACT == 1) {
; #pragma unroll
;                         for (int j = 0; j < 4; ++j) { const float a0 = fmaxf(v0[j], 0.f), a1 = fmaxf(v1[j], 0.f); v0[j] = a0 * a0; v1[j] = a1 * a1; } }
;                     u32x4 w; w.x = pk2(v0[0], v0[1]); w.y = pk2(v0[2], v0[3]); w.z = pk2(v1[0], v1[1]); w.w = pk2(v1[2], v1[3]);
;                     *(u32x4*)(rowp + bj * HALF) = w; } }
; template <class Epi>
; __device__ __forceinline__ void gemm_phase(LAS unsigned char* lds, const Gemm g, const StaticOrder& S, const Epi& E) {
;     ...
;             PG8_BAR; PG8_WAIT_L(0); PG8_MMA(1, 0, At, B0); PG8_BAR; PG8_SCHED;
;             PG8_STAGE(PG8_SB(1, 1), b3 + hstepB, voffB);
;             PG8_WAIT_V(6); PG8_BAR; PG8_MMA(1, 1, At, B1); PG8_BAR;
	s_waitcnt lgkmcnt(0)
	s_setprio 1
	s_waitcnt lgkmcnt(0)
	v_mfma_f32_16x16x32_bf16 v[28:31], v[146:149], v[174:177], v[28:31]
	v_mfma_f32_16x16x32_bf16 v[24:27], v[158:161], v[174:177], v[24:27]
	v_mfma_f32_16x16x32_bf16 v[20:23], v[146:149], v[182:185], v[20:23]
	v_mfma_f32_16x16x32_bf16 v[16:19], v[158:161], v[182:185], v[16:19]
	v_mfma_f32_16x16x32_bf16 v[12:15], v[146:149], v[190:193], v[12:15]
	v_mfma_f32_16x16x32_bf16 v[8:11], v[158:161], v[190:193], v[8:11]
	v_mfma_f32_16x16x32_bf16 v[4:7], v[146:149], v[198:201], v[4:7]
	v_mfma_f32_16x16x32_bf16 v[0:3], v[158:161], v[198:201], v[0:3]
	v_mfma_f32_16x16x32_bf16 v[28:31], v[154:157], v[178:181], v[28:31]
	v_mfma_f32_16x16x32_bf16 v[24:27], v[162:165], v[178:181], v[24:27]
	v_mfma_f32_16x16x32_bf16 v[20:23], v[154:157], v[186:189], v[20:23]
	v_mfma_f32_16x16x32_bf16 v[16:19], v[162:165], v[186:189], v[16:19]
	v_mfma_f32_16x16x32_bf16 v[12:15], v[154:157], v[194:197], v[12:15]
	v_mfma_f32_16x16x32_bf16 v[8:11], v[162:165], v[194:197], v[8:11]
	v_mfma_f32_16x16x32_bf16 v[4:7], v[154:157], v[202:205], v[4:7]
	v_mfma_f32_16x16x32_bf16 v[0:3], v[162:165], v[202:205], v[0:3]
	s_setprio 0
	s_barrier
	s_add_u32 s22, s22, 0x40080
	s_addc_u32 s23, s23, 0
	s_add_i32 s24, s24, s27
	v_lshl_add_u64 v[146:147], s[22:23], 0, v[132:133]
	s_mov_b32 m0, s24
	s_nop 0
	global_load_lds_dwordx4 v[146:147], off
	v_lshl_add_u64 v[146:147], s[22:23], 0, v[128:129]
	s_add_i32 m0, s24, 0x2000
	s_nop 0
	global_load_lds_dwordx4 v[146:147], off
	s_waitcnt vmcnt(6)
	s_barrier
	s_setprio 1
	v_mfma_f32_16x16x32_bf16 v[92:95], v[206:209], v[174:177], v[92:95]
	v_mfma_f32_16x16x32_bf16 v[88:91], v[214:217], v[174:177], v[88:91]
	v_mfma_f32_16x16x32_bf16 v[84:87], v[206:209], v[182:185], v[84:87]
	v_mfma_f32_16x16x32_bf16 v[80:83], v[214:217], v[182:185], v[80:83]
	v_mfma_f32_16x16x32_bf16 v[72:75], v[206:209], v[190:193], v[72:75]
	v_mfma_f32_16x16x32_bf16 v[68:71], v[214:217], v[190:193], v[68:71]
	v_mfma_f32_16x16x32_bf16 v[52:55], v[206:209], v[198:201], v[52:55]
	v_mfma_f32_16x16x32_bf16 v[44:47], v[214:217], v[198:201], v[44:47]
	v_mfma_f32_16x16x32_bf16 v[92:95], v[210:213], v[178:181], v[92:95]
	v_mfma_f32_16x16x32_bf16 v[88:91], v[218:221], v[178:181], v[88:91]
	v_mfma_f32_16x16x32_bf16 v[84:87], v[210:213], v[186:189], v[84:87]
	v_mfma_f32_16x16x32_bf16 v[80:83], v[218:221], v[186:189], v[80:83]
	v_mfma_f32_16x16x32_bf16 v[72:75], v[210:213], v[194:197], v[72:75]
	v_mfma_f32_16x16x32_bf16 v[68:71], v[218:221], v[194:197], v[68:71]
	v_mfma_f32_16x16x32_bf16 v[52:55], v[210:213], v[202:205], v[52:55]
	v_mfma_f32_16x16x32_bf16 v[44:47], v[218:221], v[202:205], v[44:47]
	s_setprio 0
	s_add_i32 s47, s47, 2
	s_add_u32 s20, s20, 0x100
	s_addc_u32 s21, s21, 0
	s_add_u32 s45, s45, 0x100
	s_addc_u32 s46, s46, 0
	s_cmp_gt_u32 s47, 13
	s_barrier
	s_cbranch_scc0 .LBB0_205
	s_bfe_u32 vcc_lo, s18, 0x20003
	s_lshl_b32 vcc_lo, vcc_lo, 10
	s_add_i32 vcc_lo, vcc_lo, 0x20010
	v_lshl_add_u32 v236, v153, 2, vcc_lo
	ds_read_b32 v228, v236
	ds_read_b32 v229, v236 offset:64
	ds_read_b32 v230, v236 offset:128
	ds_read_b32 v231, v236 offset:192
	ds_read_b32 v232, v236 offset:512
	ds_read_b32 v233, v236 offset:576
	ds_read_b32 v234, v236 offset:640
	ds_read_b32 v235, v236 offset:704
	s_waitcnt lgkmcnt(0)
	v_lshl_add_u32 v162, s18, 8, v153
	v_ashrrev_i32_e32 v163, 31, v162
	v_or_b32_e32 v160, 16, v162
	v_or_b32_e32 v158, 32, v162
	v_or_b32_e32 v156, 48, v162
	v_ashrrev_i32_e32 v161, 31, v160
	v_ashrrev_i32_e32 v159, 31, v158
	v_ashrrev_i32_e32 v157, 31, v156
	v_add_u32_e32 v154, 0x80, v162
	v_add_u32_e32 v150, 0x90, v162
	v_add_u32_e32 v148, 0xa0, v162
	v_add_u32_e32 v146, 0xb0, v162
	v_ashrrev_i32_e32 v155, 31, v154
	v_ashrrev_i32_e32 v151, 31, v150
	v_ashrrev_i32_e32 v149, 31, v148
	v_ashrrev_i32_e32 v147, 31, v146
	s_cmp_lg_u32 s43, 20
	s_mov_b64 s[18:19], -1
	s_cbranch_scc0 .LBB0_208
	v_and_b32_e32 v236, 8, v153
	v_sub_u32_e32 v162, v162, v236
	v_sub_u32_e32 v160, v160, v236
	v_sub_u32_e32 v158, v158, v236
	v_sub_u32_e32 v156, v156, v236
	v_sub_u32_e32 v154, v154, v236
	v_sub_u32_e32 v150, v150, v236
	v_sub_u32_e32 v148, v148, v236
	v_sub_u32_e32 v146, v146, v236
	s_mov_b32 vcc_lo, 0x14000
	s_mov_b32 vcc_hi, 0
	s_waitcnt vmcnt(8)
	v_and_b32_e32 v237, 0x60, v169
	v_lshlrev_b32_e32 v237, 1, v237
	v_and_b32_e32 v238, 0x18, v169
	v_or_b32_e32 v237, v237, v238
	v_lshl_or_b32 v237, v236, 2, v237
	v_lshl_or_b32 v166, s43, 8, v237
	v_ashrrev_i32_e32 v167, 31, v166
	v_lshlrev_b64 v[166:167], 1, v[166:167]
	v_mov_b32_e32 v186, v228
	v_mov_b64_e32 v[164:165], s[96:97]
	v_mad_i64_i32 v[182:183], s[18:19], v162, s42, v[164:165]
	v_lshl_add_u64 v[188:189], v[182:183], 0, v[166:167]
	v_pk_mul_f32 v[184:185], v[78:79], v[186:187] op_sel_hi:[1,0]
	v_pk_mul_f32 v[182:183], v[76:77], v[186:187] op_sel_hi:[1,0]
	v_pk_mul_f32 v[190:191], v[66:67], v[186:187] op_sel_hi:[1,0]
	v_pk_mul_f32 v[192:193], v[64:65], v[186:187] op_sel_hi:[1,0]
	v_cvt_pk_bf16_f32 v238, v182, v183
	v_cvt_pk_bf16_f32 v239, v184, v185
	v_cvt_pk_bf16_f32 v240, v192, v193
	v_cvt_pk_bf16_f32 v241, v190, v191
	v_pk_mul_f32 v[124:125], v[124:125], v[186:187] op_sel_hi:[1,0]
	v_pk_mul_f32 v[126:127], v[126:127], v[186:187] op_sel_hi:[1,0]
	s_nop 0
	v_pk_mul_f32 v[182:183], v[122:123], v[186:187] op_sel_hi:[1,0]
	v_pk_mul_f32 v[122:123], v[120:121], v[186:187] op_sel_hi:[1,0]
	v_cvt_pk_bf16_f32 v242, v124, v125
	v_cvt_pk_bf16_f32 v243, v126, v127
	v_cvt_pk_bf16_f32 v244, v122, v123
	v_cvt_pk_bf16_f32 v245, v182, v183
	v_mov_b32_e32 v246, v238
	v_mov_b32_e32 v247, v239
	v_mov_b32_e32 v248, v240
	v_mov_b32_e32 v249, v241
	v_mov_b32_dpp v238, v242 row_shr:8 row_mask:0xf bank_mask:0xc
; __device__ __forceinline__ unsigned pk2(float lo, float hi) { const f32x2 v = (f32x2){lo, hi}; const bf16x2_t b = __builtin_convertvector(v, bf16x2_t); return __builtin_bit_cast(unsigned, b); }
;     __device__ __forceinline__ void operator()(const f32x4 (&acc)[2][2][4][2], const Unit& u, int wr, int wc, int fr, int fq, const float (&)[8]) const {
;     ...
;         const int col0 = u.pn * BM + wc * 32 + 8 * fq;
; #pragma unroll
;         for (int ai = 0; ai < 2; ++ai)
; #pragma unroll
;             for (int m = 0; m < 4; ++m) { const int row = row0 + ai * HALF + m * 16; const float rs = rsqrtf(ep[ai * 4 + m] * (1.0f / 1024.0f) + EPS);
;                 u16* rowp = O + (size_t)row * ldc + col0;
; #pragma unroll
;                 for (int bj = 0; bj < 2; ++bj) { f32x4 v0 = acc[ai][bj][m][0] * rs, v1 = acc[ai][bj][m][1] * rs;
;                     if (ACT == 1) {
; #pragma unroll
;                         for (int j = 0; j < 4; ++j) { const float a0 = fmaxf(v0[j], 0.f), a1 = fmaxf(v1[j], 0.f); v0[j] = a0 * a0; v1[j] = a1 * a1; } }
;                     u32x4 w; w.x = pk2(v0[0], v0[1]); w.y = pk2(v0[2], v0[3]); w.z = pk2(v1[0], v1[1]); w.w = pk2(v1[2], v1[3]);
;                     *(u32x4*)(rowp + bj * HALF) = w; } }
	v_mov_b32_dpp v239, v243 row_shr:8 row_mask:0xf bank_mask:0xc
	v_mov_b32_dpp v240, v244 row_shr:8 row_mask:0xf bank_mask:0xc
	v_mov_b32_dpp v241, v245 row_shr:8 row_mask:0xf bank_mask:0xc
	global_store_dwordx4 v[188:189], v[238:241], off
	v_lshl_add_u64 v[236:237], v[188:189], 0, vcc
	v_mov_b32_dpp v242, v246 row_shl:8 row_mask:0xf bank_mask:0x3
	v_mov_b32_dpp v243, v247 row_shl:8 row_mask:0xf bank_mask:0x3
	v_mov_b32_dpp v244, v248 row_shl:8 row_mask:0xf bank_mask:0x3
	v_mov_b32_dpp v245, v249 row_shl:8 row_mask:0xf bank_mask:0x3
	global_store_dwordx4 v[236:237], v[242:245], off
	s_nop 1
	v_mov_b32_e32 v124, v229
	v_mad_i64_i32 v[120:121], s[18:19], v160, s42, v[164:165]
	v_lshl_add_u64 v[126:127], v[120:121], 0, v[166:167]
	v_pk_mul_f32 v[122:123], v[62:63], v[124:125] op_sel_hi:[1,0]
	v_pk_mul_f32 v[120:121], v[60:61], v[124:125] op_sel_hi:[1,0]
	v_pk_mul_f32 v[182:183], v[58:59], v[124:125] op_sel_hi:[1,0]
	v_pk_mul_f32 v[184:185], v[56:57], v[124:125] op_sel_hi:[1,0]
	v_cvt_pk_bf16_f32 v238, v120, v121
	v_cvt_pk_bf16_f32 v239, v122, v123
	v_cvt_pk_bf16_f32 v240, v184, v185
	v_cvt_pk_bf16_f32 v241, v182, v183
	v_pk_mul_f32 v[116:117], v[116:117], v[124:125] op_sel_hi:[1,0]
	v_pk_mul_f32 v[118:119], v[118:119], v[124:125] op_sel_hi:[1,0]
	s_nop 0
	v_pk_mul_f32 v[120:121], v[114:115], v[124:125] op_sel_hi:[1,0]
	v_pk_mul_f32 v[114:115], v[112:113], v[124:125] op_sel_hi:[1,0]
	v_cvt_pk_bf16_f32 v242, v116, v117
	v_cvt_pk_bf16_f32 v243, v118, v119
	v_cvt_pk_bf16_f32 v244, v114, v115
	v_cvt_pk_bf16_f32 v245, v120, v121
	v_mov_b32_e32 v246, v238
	v_mov_b32_e32 v247, v239
	v_mov_b32_e32 v248, v240
	v_mov_b32_e32 v249, v241
	v_mov_b32_dpp v238, v242 row_shr:8 row_mask:0xf bank_mask:0xc
	v_mov_b32_dpp v239, v243 row_shr:8 row_mask:0xf bank_mask:0xc
	v_mov_b32_dpp v240, v244 row_shr:8 row_mask:0xf bank_mask:0xc
	v_mov_b32_dpp v241, v245 row_shr:8 row_mask:0xf bank_mask:0xc
	global_store_dwordx4 v[126:127], v[238:241], off
	v_lshl_add_u64 v[236:237], v[126:127], 0, vcc
	v_mov_b32_dpp v242, v246 row_shl:8 row_mask:0xf bank_mask:0x3
	v_mov_b32_dpp v243, v247 row_shl:8 row_mask:0xf bank_mask:0x3
	v_mov_b32_dpp v244, v248 row_shl:8 row_mask:0xf bank_mask:0x3
	v_mov_b32_dpp v245, v249 row_shl:8 row_mask:0xf bank_mask:0x3
	global_store_dwordx4 v[236:237], v[242:245], off
	s_nop 1
	v_mov_b32_e32 v116, v230
	v_mad_i64_i32 v[112:113], s[18:19], v158, s42, v[164:165]
	v_lshl_add_u64 v[118:119], v[112:113], 0, v[166:167]
	v_pk_mul_f32 v[114:115], v[50:51], v[116:117] op_sel_hi:[1,0]
	v_pk_mul_f32 v[112:113], v[48:49], v[116:117] op_sel_hi:[1,0]
	v_pk_mul_f32 v[120:121], v[42:43], v[116:117] op_sel_hi:[1,0]
	v_pk_mul_f32 v[122:123], v[40:41], v[116:117] op_sel_hi:[1,0]
	v_cvt_pk_bf16_f32 v238, v112, v113
	v_cvt_pk_bf16_f32 v239, v114, v115
	v_cvt_pk_bf16_f32 v240, v122, v123
	v_cvt_pk_bf16_f32 v241, v120, v121
	v_pk_mul_f32 v[108:109], v[108:109], v[116:117] op_sel_hi:[1,0]
	v_pk_mul_f32 v[110:111], v[110:111], v[116:117] op_sel_hi:[1,0]
	s_nop 0
	v_pk_mul_f32 v[112:113], v[106:107], v[116:117] op_sel_hi:[1,0]
	v_pk_mul_f32 v[106:107], v[104:105], v[116:117] op_sel_hi:[1,0]
	v_cvt_pk_bf16_f32 v242, v108, v109
	v_cvt_pk_bf16_f32 v243, v110, v111
	v_cvt_pk_bf16_f32 v244, v106, v107
	v_cvt_pk_bf16_f32 v245, v112, v113
	v_mov_b32_e32 v246, v238
	v_mov_b32_e32 v247, v239
	v_mov_b32_e32 v248, v240
	v_mov_b32_e32 v249, v241
	v_mov_b32_dpp v238, v242 row_shr:8 row_mask:0xf bank_mask:0xc
	v_mov_b32_dpp v239, v243 row_shr:8 row_mask:0xf bank_mask:0xc
	v_mov_b32_dpp v240, v244 row_shr:8 row_mask:0xf bank_mask:0xc
	v_mov_b32_dpp v241, v245 row_shr:8 row_mask:0xf bank_mask:0xc
	global_store_dwordx4 v[118:119], v[238:241], off
	v_lshl_add_u64 v[236:237], v[118:119], 0, vcc
	v_mov_b32_dpp v242, v246 row_shl:8 row_mask:0xf bank_mask:0x3
	v_mov_b32_dpp v243, v247 row_shl:8 row_mask:0xf bank_mask:0x3
	v_mov_b32_dpp v244, v248 row_shl:8 row_mask:0xf bank_mask:0x3
	v_mov_b32_dpp v245, v249 row_shl:8 row_mask:0xf bank_mask:0x3
	global_store_dwordx4 v[236:237], v[242:245], off
	s_nop 1
	v_mov_b32_e32 v108, v231
	v_mad_i64_i32 v[104:105], s[18:19], v156, s42, v[164:165]
	v_lshl_add_u64 v[110:111], v[104:105], 0, v[166:167]
	v_pk_mul_f32 v[106:107], v[38:39], v[108:109] op_sel_hi:[1,0]
	v_pk_mul_f32 v[104:105], v[36:37], v[108:109] op_sel_hi:[1,0]
	v_pk_mul_f32 v[112:113], v[34:35], v[108:109] op_sel_hi:[1,0]
	v_pk_mul_f32 v[114:115], v[32:33], v[108:109] op_sel_hi:[1,0]
	v_cvt_pk_bf16_f32 v238, v104, v105
	v_cvt_pk_bf16_f32 v239, v106, v107
	v_cvt_pk_bf16_f32 v240, v114, v115
	v_cvt_pk_bf16_f32 v241, v112, v113
	v_pk_mul_f32 v[100:101], v[100:101], v[108:109] op_sel_hi:[1,0]
	v_pk_mul_f32 v[102:103], v[102:103], v[108:109] op_sel_hi:[1,0]
	s_nop 0
	v_pk_mul_f32 v[104:105], v[98:99], v[108:109] op_sel_hi:[1,0]
	v_pk_mul_f32 v[98:99], v[96:97], v[108:109] op_sel_hi:[1,0]
	v_cvt_pk_bf16_f32 v242, v100, v101
	v_cvt_pk_bf16_f32 v243, v102, v103
	v_cvt_pk_bf16_f32 v244, v98, v99
	v_cvt_pk_bf16_f32 v245, v104, v105
	v_mov_b32_e32 v246, v238
	v_mov_b32_e32 v247, v239
	v_mov_b32_e32 v248, v240
	v_mov_b32_e32 v249, v241
	v_mov_b32_dpp v238, v242 row_shr:8 row_mask:0xf bank_mask:0xc
	v_mov_b32_dpp v239, v243 row_shr:8 row_mask:0xf bank_mask:0xc
	v_mov_b32_dpp v240, v244 row_shr:8 row_mask:0xf bank_mask:0xc
	v_mov_b32_dpp v241, v245 row_shr:8 row_mask:0xf bank_mask:0xc
	global_store_dwordx4 v[110:111], v[238:241], off
	v_lshl_add_u64 v[236:237], v[110:111], 0, vcc
	v_mov_b32_dpp v242, v246 row_shl:8 row_mask:0xf bank_mask:0x3
	v_mov_b32_dpp v243, v247 row_shl:8 row_mask:0xf bank_mask:0x3
	v_mov_b32_dpp v244, v248 row_shl:8 row_mask:0xf bank_mask:0x3
	v_mov_b32_dpp v245, v249 row_shl:8 row_mask:0xf bank_mask:0x3
; __device__ __forceinline__ unsigned pk2(float lo, float hi) { const f32x2 v = (f32x2){lo, hi}; const bf16x2_t b = __builtin_convertvector(v, bf16x2_t); return __builtin_bit_cast(unsigned, b); }
;     __device__ __forceinline__ void operator()(const f32x4 (&acc)[2][2][4][2], const Unit& u, int wr, int wc, int fr, int fq, const float (&)[8]) const {
;     ...
;         const int col0 = u.pn * BM + wc * 32 + 8 * fq;
; #pragma unroll
;         for (int ai = 0; ai < 2; ++ai)
; #pragma unroll
;             for (int m = 0; m < 4; ++m) { const int row = row0 + ai * HALF + m * 16; const float rs = rsqrtf(ep[ai * 4 + m] * (1.0f / 1024.0f) + EPS);
;                 u16* rowp = O + (size_t)row * ldc + col0;
; #pragma unroll
;                 for (int bj = 0; bj < 2; ++bj) { f32x4 v0 = acc[ai][bj][m][0] * rs, v1 = acc[ai][bj][m][1] * rs;
;                     if (ACT == 1) {
; #pragma unroll
;                         for (int j = 0; j < 4; ++j) { const float a0 = fmaxf(v0[j], 0.f), a1 = fmaxf(v1[j], 0.f); v0[j] = a0 * a0; v1[j] = a1 * a1; } }
;                     u32x4 w; w.x = pk2(v0[0], v0[1]); w.y = pk2(v0[2], v0[3]); w.z = pk2(v1[0], v1[1]); w.w = pk2(v1[2], v1[3]);
;                     *(u32x4*)(rowp + bj * HALF) = w; } }
	global_store_dwordx4 v[236:237], v[242:245], off
	s_nop 1
	v_mov_b32_e32 v100, v232
	v_mad_i64_i32 v[96:97], s[18:19], v154, s42, v[164:165]
	v_lshl_add_u64 v[102:103], v[96:97], 0, v[166:167]
	v_pk_mul_f32 v[98:99], v[30:31], v[100:101] op_sel_hi:[1,0]
	v_pk_mul_f32 v[96:97], v[28:29], v[100:101] op_sel_hi:[1,0]
	v_pk_mul_f32 v[104:105], v[26:27], v[100:101] op_sel_hi:[1,0]
	v_pk_mul_f32 v[106:107], v[24:25], v[100:101] op_sel_hi:[1,0]
	v_cvt_pk_bf16_f32 v238, v96, v97
	v_cvt_pk_bf16_f32 v239, v98, v99
	v_cvt_pk_bf16_f32 v240, v106, v107
	v_cvt_pk_bf16_f32 v241, v104, v105
	v_pk_mul_f32 v[92:93], v[92:93], v[100:101] op_sel_hi:[1,0]
	v_pk_mul_f32 v[94:95], v[94:95], v[100:101] op_sel_hi:[1,0]
	s_nop 0
	v_pk_mul_f32 v[96:97], v[90:91], v[100:101] op_sel_hi:[1,0]
	v_pk_mul_f32 v[90:91], v[88:89], v[100:101] op_sel_hi:[1,0]
	v_cvt_pk_bf16_f32 v242, v92, v93
	v_cvt_pk_bf16_f32 v243, v94, v95
	v_cvt_pk_bf16_f32 v244, v90, v91
	v_cvt_pk_bf16_f32 v245, v96, v97
	v_mov_b32_e32 v246, v238
	v_mov_b32_e32 v247, v239
	v_mov_b32_e32 v248, v240
	v_mov_b32_e32 v249, v241
	v_mov_b32_dpp v238, v242 row_shr:8 row_mask:0xf bank_mask:0xc
	v_mov_b32_dpp v239, v243 row_shr:8 row_mask:0xf bank_mask:0xc
	v_mov_b32_dpp v240, v244 row_shr:8 row_mask:0xf bank_mask:0xc
	v_mov_b32_dpp v241, v245 row_shr:8 row_mask:0xf bank_mask:0xc
	global_store_dwordx4 v[102:103], v[238:241], off
	v_lshl_add_u64 v[236:237], v[102:103], 0, vcc
	v_mov_b32_dpp v242, v246 row_shl:8 row_mask:0xf bank_mask:0x3
	v_mov_b32_dpp v243, v247 row_shl:8 row_mask:0xf bank_mask:0x3
	v_mov_b32_dpp v244, v248 row_shl:8 row_mask:0xf bank_mask:0x3
	v_mov_b32_dpp v245, v249 row_shl:8 row_mask:0xf bank_mask:0x3
	global_store_dwordx4 v[236:237], v[242:245], off
	s_nop 1
	v_mov_b32_e32 v92, v233
	v_mad_i64_i32 v[88:89], s[18:19], v150, s42, v[164:165]
	v_lshl_add_u64 v[94:95], v[88:89], 0, v[166:167]
	v_pk_mul_f32 v[90:91], v[22:23], v[92:93] op_sel_hi:[1,0]
	v_pk_mul_f32 v[88:89], v[20:21], v[92:93] op_sel_hi:[1,0]
	v_pk_mul_f32 v[96:97], v[18:19], v[92:93] op_sel_hi:[1,0]
	v_pk_mul_f32 v[98:99], v[16:17], v[92:93] op_sel_hi:[1,0]
	v_cvt_pk_bf16_f32 v238, v88, v89
	v_cvt_pk_bf16_f32 v239, v90, v91
	v_cvt_pk_bf16_f32 v240, v98, v99
	v_cvt_pk_bf16_f32 v241, v96, v97
	v_pk_mul_f32 v[84:85], v[84:85], v[92:93] op_sel_hi:[1,0]
	v_pk_mul_f32 v[86:87], v[86:87], v[92:93] op_sel_hi:[1,0]
	s_nop 0
	v_pk_mul_f32 v[88:89], v[82:83], v[92:93] op_sel_hi:[1,0]
	v_pk_mul_f32 v[82:83], v[80:81], v[92:93] op_sel_hi:[1,0]
	v_cvt_pk_bf16_f32 v242, v84, v85
	v_cvt_pk_bf16_f32 v243, v86, v87
	v_cvt_pk_bf16_f32 v244, v82, v83
	v_cvt_pk_bf16_f32 v245, v88, v89
	v_mov_b32_e32 v246, v238
	v_mov_b32_e32 v247, v239
	v_mov_b32_e32 v248, v240
	v_mov_b32_e32 v249, v241
	v_mov_b32_dpp v238, v242 row_shr:8 row_mask:0xf bank_mask:0xc
	v_mov_b32_dpp v239, v243 row_shr:8 row_mask:0xf bank_mask:0xc
	v_mov_b32_dpp v240, v244 row_shr:8 row_mask:0xf bank_mask:0xc
	v_mov_b32_dpp v241, v245 row_shr:8 row_mask:0xf bank_mask:0xc
	global_store_dwordx4 v[94:95], v[238:241], off
	v_lshl_add_u64 v[236:237], v[94:95], 0, vcc
	v_mov_b32_dpp v242, v246 row_shl:8 row_mask:0xf bank_mask:0x3
	v_mov_b32_dpp v243, v247 row_shl:8 row_mask:0xf bank_mask:0x3
	v_mov_b32_dpp v244, v248 row_shl:8 row_mask:0xf bank_mask:0x3
	v_mov_b32_dpp v245, v249 row_shl:8 row_mask:0xf bank_mask:0x3
	global_store_dwordx4 v[236:237], v[242:245], off
	s_nop 1
	v_mov_b32_e32 v84, v234
	v_mad_i64_i32 v[80:81], s[18:19], v148, s42, v[164:165]
	v_lshl_add_u64 v[86:87], v[80:81], 0, v[166:167]
	v_pk_mul_f32 v[82:83], v[14:15], v[84:85] op_sel_hi:[1,0]
	v_pk_mul_f32 v[80:81], v[12:13], v[84:85] op_sel_hi:[1,0]
	v_pk_mul_f32 v[88:89], v[10:11], v[84:85] op_sel_hi:[1,0]
	v_pk_mul_f32 v[90:91], v[8:9], v[84:85] op_sel_hi:[1,0]
	v_cvt_pk_bf16_f32 v238, v80, v81
	v_cvt_pk_bf16_f32 v239, v82, v83
	v_cvt_pk_bf16_f32 v240, v90, v91
	v_cvt_pk_bf16_f32 v241, v88, v89
	v_pk_mul_f32 v[72:73], v[72:73], v[84:85] op_sel_hi:[1,0]
	v_pk_mul_f32 v[74:75], v[74:75], v[84:85] op_sel_hi:[1,0]
	s_nop 0
	v_pk_mul_f32 v[80:81], v[70:71], v[84:85] op_sel_hi:[1,0]
	v_pk_mul_f32 v[70:71], v[68:69], v[84:85] op_sel_hi:[1,0]
	v_cvt_pk_bf16_f32 v242, v72, v73
	v_cvt_pk_bf16_f32 v243, v74, v75
	v_cvt_pk_bf16_f32 v244, v70, v71
	v_cvt_pk_bf16_f32 v245, v80, v81
	v_mov_b32_e32 v246, v238
	v_mov_b32_e32 v247, v239
	v_mov_b32_e32 v248, v240
	v_mov_b32_e32 v249, v241
	v_mov_b32_dpp v238, v242 row_shr:8 row_mask:0xf bank_mask:0xc
	v_mov_b32_dpp v239, v243 row_shr:8 row_mask:0xf bank_mask:0xc
	v_mov_b32_dpp v240, v244 row_shr:8 row_mask:0xf bank_mask:0xc
	v_mov_b32_dpp v241, v245 row_shr:8 row_mask:0xf bank_mask:0xc
	global_store_dwordx4 v[86:87], v[238:241], off
	v_lshl_add_u64 v[236:237], v[86:87], 0, vcc
	v_mov_b32_dpp v242, v246 row_shl:8 row_mask:0xf bank_mask:0x3
	v_mov_b32_dpp v243, v247 row_shl:8 row_mask:0xf bank_mask:0x3
	v_mov_b32_dpp v244, v248 row_shl:8 row_mask:0xf bank_mask:0x3
	v_mov_b32_dpp v245, v249 row_shl:8 row_mask:0xf bank_mask:0x3
	global_store_dwordx4 v[236:237], v[242:245], off
	s_nop 1
	v_mov_b32_e32 v72, v235
	v_mad_i64_i32 v[68:69], s[18:19], v146, s42, v[164:165]
	v_lshl_add_u64 v[74:75], v[68:69], 0, v[166:167]
	v_pk_mul_f32 v[70:71], v[6:7], v[72:73] op_sel_hi:[1,0]
	v_pk_mul_f32 v[68:69], v[4:5], v[72:73] op_sel_hi:[1,0]
	v_pk_mul_f32 v[80:81], v[2:3], v[72:73] op_sel_hi:[1,0]
	v_pk_mul_f32 v[82:83], v[0:1], v[72:73] op_sel_hi:[1,0]
	v_cvt_pk_bf16_f32 v238, v68, v69
	v_cvt_pk_bf16_f32 v239, v70, v71
	v_cvt_pk_bf16_f32 v240, v82, v83
	v_cvt_pk_bf16_f32 v241, v80, v81
	v_pk_mul_f32 v[54:55], v[54:55], v[72:73] op_sel_hi:[1,0]
	v_pk_mul_f32 v[52:53], v[52:53], v[72:73] op_sel_hi:[1,0]
	v_pk_mul_f32 v[68:69], v[46:47], v[72:73] op_sel_hi:[1,0]
	v_pk_mul_f32 v[46:47], v[44:45], v[72:73] op_sel_hi:[1,0]
	v_cvt_pk_bf16_f32 v242, v52, v53
	v_cvt_pk_bf16_f32 v243, v54, v55
	v_cvt_pk_bf16_f32 v244, v46, v47
	v_cvt_pk_bf16_f32 v245, v68, v69
	v_mov_b32_e32 v246, v238
	v_mov_b32_e32 v247, v239
	v_mov_b32_e32 v248, v240
	v_mov_b32_e32 v249, v241
	v_mov_b32_dpp v238, v242 row_shr:8 row_mask:0xf bank_mask:0xc
	v_mov_b32_dpp v239, v243 row_shr:8 row_mask:0xf bank_mask:0xc
	v_mov_b32_dpp v240, v244 row_shr:8 row_mask:0xf bank_mask:0xc
	v_mov_b32_dpp v241, v245 row_shr:8 row_mask:0xf bank_mask:0xc
	global_store_dwordx4 v[74:75], v[238:241], off
	v_lshl_add_u64 v[236:237], v[74:75], 0, vcc
	v_mov_b32_dpp v242, v246 row_shl:8 row_mask:0xf bank_mask:0x3
	v_mov_b32_dpp v243, v247 row_shl:8 row_mask:0xf bank_mask:0x3
	v_mov_b32_dpp v244, v248 row_shl:8 row_mask:0xf bank_mask:0x3
	v_mov_b32_dpp v245, v249 row_shl:8 row_mask:0xf bank_mask:0x3
	global_store_dwordx4 v[236:237], v[242:245], off
	s_mov_b64 s[18:19], 0

; #define PG8_STAGE(bufoff, gbase, voff) do { _Pragma("unroll") for (int _i = 0; _i < 2; ++_i) \
;         __builtin_amdgcn_global_load_lds((const unsigned*)((const char*)(gbase) + (voff)[_i]), (LAS unsigned*)(lds + (bufoff) + ldsw + _i * 8192), 16, 0, 0); } while (0)
; #define PG8_LDA(dst, b, h) do { _Pragma("unroll") for (int m = 0; m < 4; ++m) _Pragma("unroll") for (int k = 0; k < 2; ++k) dst[m][k] = *(const LAS bf16x8*)(lds + PG8_SA(b, h) + aoff + m * 2048 + k * 1024); } while (0)
; #define PG8_LDB(dst, b, h) do { _Pragma("unroll") for (int n = 0; n < 2; ++n) _Pragma("unroll") for (int k = 0; k < 2; ++k) dst[n][k] = *(const LAS bf16x8*)(lds + PG8_SB(b, h) + boff + n * 2048 + k * 1024); } while (0)
; #define PG8_MMA(ai, bj, At, Bt) do { __builtin_amdgcn_s_setprio(1); _Pragma("unroll") for (int m = 0; m < 4; ++m) _Pragma("unroll") for (int n = 0; n < 2; ++n) _Pragma("unroll") for (int k = 0; k < 2; ++k) \
;         acc[ai][bj][m][n] = __builtin_amdgcn_mfma_f32_16x16x32_bf16(Bt[n][k], At[m][k], acc[ai][bj][m][n], 0, 0, 0); __builtin_amdgcn_s_setprio(0); } while (0)
; #define PG8_WAIT_V(n) asm volatile("s_waitcnt vmcnt(" #n ")" ::: "memory")
; #define PG8_WAIT_L(n) asm volatile("s_waitcnt lgkmcnt(" #n ")" ::: "memory")
; #define PG8_BAR __builtin_amdgcn_s_barrier()
; #define PG8_SCHED __builtin_amdgcn_sched_barrier(0)
; template <class Epi>
; __device__ __forceinline__ void gemm_phase(LAS unsigned char* lds, const Gemm g, const StaticOrder& S, const Epi& E) {
;     ...
;             PG8_LDB(B0, 0, 0); PG8_SCHED; PG8_LDA(At, 0, 0); PG8_STAGE(PG8_SA(1, 1), a1 + hstepA, voffA);
;             PG8_WAIT_L(8); PG8_BAR; PG8_WAIT_L(0); PG8_MMA(0, 0, At, B0); PG8_BAR; PG8_SCHED;
;             PG8_LDB(B1, 0, 1); PG8_STAGE(PG8_SB(0, 0), b2, voffB);
;             PG8_BAR; PG8_WAIT_L(0); PG8_MMA(0, 1, At, B1); PG8_BAR;
;             PG8_LDA(At, 0, 1); PG8_STAGE(PG8_SA(0, 0), a2, voffA);
;             PG8_BAR; PG8_WAIT_L(0); PG8_MMA(1, 0, At, B0); PG8_BAR; PG8_SCHED;
;             PG8_STAGE(PG8_SB(0, 1), b2 + hstepB, voffB);
;             PG8_WAIT_V(6); PG8_BAR; PG8_MMA(1, 1, At, B1); PG8_BAR;
.LBB0_922:
	ds_read_b128 v[146:149], v173
	ds_read_b128 v[154:157], v173 offset:1024
	ds_read_b128 v[158:161], v173 offset:2048
	ds_read_b128 v[162:165], v173 offset:3072
	s_add_u32 s22, s20, 0xfffc0080
	s_addc_u32 s23, s21, -1
	s_cmp_eq_u32 s47, 12
	s_cselect_b32 s25, s13, s23
	s_cselect_b32 s24, s43, s22
	s_cselect_b32 s23, s11, s46
	s_cselect_b32 s22, s44, s45
	v_lshl_add_u64 v[150:151], s[20:21], 0, v[138:139]
	s_add_i32 m0, s19, 0xc000
	ds_read_b128 v[166:169], v174
	ds_read_b128 v[178:181], v174 offset:1024
	ds_read_b128 v[182:185], v174 offset:2048
	ds_read_b128 v[186:189], v174 offset:3072
	ds_read_b128 v[190:193], v174 offset:4096
	ds_read_b128 v[194:197], v174 offset:5120
	ds_read_b128 v[198:201], v174 offset:6144
	ds_read_b128 v[202:205], v174 offset:7168
	global_load_lds_dwordx4 v[150:151], off
	v_lshl_add_u64 v[150:151], s[20:21], 0, v[140:141]
	s_add_i32 m0, s19, 0xe000
	s_nop 0
	global_load_lds_dwordx4 v[150:151], off
	s_waitcnt lgkmcnt(8)
	s_barrier
	s_waitcnt lgkmcnt(0)
	s_setprio 1
	s_waitcnt lgkmcnt(0)
	v_mfma_f32_16x16x32_bf16 v[124:127], v[146:149], v[166:169], v[124:127]
	v_mfma_f32_16x16x32_bf16 v[120:123], v[158:161], v[166:169], v[120:123]
	v_mfma_f32_16x16x32_bf16 v[112:115], v[146:149], v[182:185], v[112:115]
	v_mfma_f32_16x16x32_bf16 v[104:107], v[158:161], v[182:185], v[104:107]
	v_mfma_f32_16x16x32_bf16 v[92:95], v[146:149], v[190:193], v[92:95]
	v_mfma_f32_16x16x32_bf16 v[88:91], v[158:161], v[190:193], v[88:91]
	v_mfma_f32_16x16x32_bf16 v[80:83], v[146:149], v[198:201], v[80:83]
	v_mfma_f32_16x16x32_bf16 v[72:75], v[158:161], v[198:201], v[72:75]
	v_mfma_f32_16x16x32_bf16 v[124:127], v[154:157], v[178:181], v[124:127]
	v_mfma_f32_16x16x32_bf16 v[120:123], v[162:165], v[178:181], v[120:123]
	v_mfma_f32_16x16x32_bf16 v[112:115], v[154:157], v[186:189], v[112:115]
	v_mfma_f32_16x16x32_bf16 v[104:107], v[162:165], v[186:189], v[104:107]
	v_mfma_f32_16x16x32_bf16 v[92:95], v[154:157], v[194:197], v[92:95]
	v_mfma_f32_16x16x32_bf16 v[88:91], v[162:165], v[194:197], v[88:91]
	v_mfma_f32_16x16x32_bf16 v[80:83], v[154:157], v[202:205], v[80:83]
	v_mfma_f32_16x16x32_bf16 v[72:75], v[162:165], v[202:205], v[72:75]
	s_setprio 0
	s_barrier
	s_add_i32 s48, s38, s27
	v_lshl_add_u64 v[150:151], s[22:23], 0, v[132:133]
	s_mov_b32 m0, s48
	ds_read_b128 v[206:209], v175
	ds_read_b128 v[210:213], v175 offset:1024
	ds_read_b128 v[214:217], v175 offset:2048
	ds_read_b128 v[218:221], v175 offset:3072
	global_load_lds_dwordx4 v[150:151], off
	v_lshl_add_u64 v[222:223], s[22:23], 0, v[128:129]
	s_add_i32 m0, s48, 0x2000
	s_nop 0
	global_load_lds_dwordx4 v[222:223], off
	s_barrier
	s_waitcnt lgkmcnt(0)
	s_setprio 1
	s_waitcnt lgkmcnt(0)
	v_mfma_f32_16x16x32_bf16 v[116:119], v[206:209], v[166:169], v[116:119]
	v_mfma_f32_16x16x32_bf16 v[108:111], v[214:217], v[166:169], v[108:111]
	v_mfma_f32_16x16x32_bf16 v[100:103], v[206:209], v[182:185], v[100:103]
	v_mfma_f32_16x16x32_bf16 v[96:99], v[214:217], v[182:185], v[96:99]
	v_mfma_f32_16x16x32_bf16 v[84:87], v[206:209], v[190:193], v[84:87]
	v_mfma_f32_16x16x32_bf16 v[76:79], v[214:217], v[190:193], v[76:79]
	v_mfma_f32_16x16x32_bf16 v[68:71], v[206:209], v[198:201], v[68:71]
	v_mfma_f32_16x16x32_bf16 v[64:67], v[214:217], v[198:201], v[64:67]
	v_mfma_f32_16x16x32_bf16 v[116:119], v[210:213], v[178:181], v[116:119]
	v_mfma_f32_16x16x32_bf16 v[108:111], v[218:221], v[178:181], v[108:111]
	v_mfma_f32_16x16x32_bf16 v[100:103], v[210:213], v[186:189], v[100:103]
	v_mfma_f32_16x16x32_bf16 v[96:99], v[218:221], v[186:189], v[96:99]
	v_mfma_f32_16x16x32_bf16 v[84:87], v[210:213], v[194:197], v[84:87]
	v_mfma_f32_16x16x32_bf16 v[76:79], v[218:221], v[194:197], v[76:79]
	v_mfma_f32_16x16x32_bf16 v[68:71], v[210:213], v[202:205], v[68:71]
	v_mfma_f32_16x16x32_bf16 v[64:67], v[218:221], v[202:205], v[64:67]
	s_setprio 0
	s_mov_b32 m0, s19
	v_lshl_add_u64 v[224:225], s[24:25], 0, v[134:135]
	s_barrier
	ds_read_b128 v[166:169], v174 offset:16384
	ds_read_b128 v[178:181], v174 offset:17408
	ds_read_b128 v[182:185], v174 offset:18432
	ds_read_b128 v[186:189], v174 offset:19456
	ds_read_b128 v[190:193], v174 offset:20480
	ds_read_b128 v[194:197], v174 offset:21504
	ds_read_b128 v[198:201], v174 offset:22528
	ds_read_b128 v[202:205], v174 offset:23552
	global_load_lds_dwordx4 v[224:225], off
	v_lshl_add_u64 v[226:227], s[24:25], 0, v[130:131]
	s_mov_b32 m0, s30
	s_nop 0
	global_load_lds_dwordx4 v[226:227], off
	s_barrier
	s_waitcnt lgkmcnt(0)
	s_setprio 1
	s_waitcnt lgkmcnt(0)
	v_mfma_f32_16x16x32_bf16 v[60:63], v[146:149], v[166:169], v[60:63]
	v_mfma_f32_16x16x32_bf16 v[56:59], v[158:161], v[166:169], v[56:59]
	v_mfma_f32_16x16x32_bf16 v[48:51], v[146:149], v[182:185], v[48:51]
	v_mfma_f32_16x16x32_bf16 v[40:43], v[158:161], v[182:185], v[40:43]
	v_mfma_f32_16x16x32_bf16 v[32:35], v[146:149], v[190:193], v[32:35]
	v_mfma_f32_16x16x32_bf16 v[24:27], v[158:161], v[190:193], v[24:27]
	v_mfma_f32_16x16x32_bf16 v[16:19], v[146:149], v[198:201], v[16:19]
	v_mfma_f32_16x16x32_bf16 v[8:11], v[158:161], v[198:201], v[8:11]
	v_mfma_f32_16x16x32_bf16 v[60:63], v[154:157], v[178:181], v[60:63]
	v_mfma_f32_16x16x32_bf16 v[56:59], v[162:165], v[178:181], v[56:59]
	v_mfma_f32_16x16x32_bf16 v[48:51], v[154:157], v[186:189], v[48:51]
	v_mfma_f32_16x16x32_bf16 v[40:43], v[162:165], v[186:189], v[40:43]
	v_mfma_f32_16x16x32_bf16 v[32:35], v[154:157], v[194:197], v[32:35]
	v_mfma_f32_16x16x32_bf16 v[24:27], v[162:165], v[194:197], v[24:27]
	v_mfma_f32_16x16x32_bf16 v[16:19], v[154:157], v[202:205], v[16:19]
	v_mfma_f32_16x16x32_bf16 v[8:11], v[162:165], v[202:205], v[8:11]
	s_setprio 0
	s_barrier
; #define PG8_STAGE(bufoff, gbase, voff) do { _Pragma("unroll") for (int _i = 0; _i < 2; ++_i) \
;         __builtin_amdgcn_global_load_lds((const unsigned*)((const char*)(gbase) + (voff)[_i]), (LAS unsigned*)(lds + (bufoff) + ldsw + _i * 8192), 16, 0, 0); } while (0)
; #define PG8_LDA(dst, b, h) do { _Pragma("unroll") for (int m = 0; m < 4; ++m) _Pragma("unroll") for (int k = 0; k < 2; ++k) dst[m][k] = *(const LAS bf16x8*)(lds + PG8_SA(b, h) + aoff + m * 2048 + k * 1024); } while (0)
; #define PG8_LDB(dst, b, h) do { _Pragma("unroll") for (int n = 0; n < 2; ++n) _Pragma("unroll") for (int k = 0; k < 2; ++k) dst[n][k] = *(const LAS bf16x8*)(lds + PG8_SB(b, h) + boff + n * 2048 + k * 1024); } while (0)
; #define PG8_MMA(ai, bj, At, Bt) do { __builtin_amdgcn_s_setprio(1); _Pragma("unroll") for (int m = 0; m < 4; ++m) _Pragma("unroll") for (int n = 0; n < 2; ++n) _Pragma("unroll") for (int k = 0; k < 2; ++k) \
;         acc[ai][bj][m][n] = __builtin_amdgcn_mfma_f32_16x16x32_bf16(Bt[n][k], At[m][k], acc[ai][bj][m][n], 0, 0, 0); __builtin_amdgcn_s_setprio(0); } while (0)
; #define PG8_WAIT_V(n) asm volatile("s_waitcnt vmcnt(" #n ")" ::: "memory")
; #define PG8_WAIT_L(n) asm volatile("s_waitcnt lgkmcnt(" #n ")" ::: "memory")
; #define PG8_BAR __builtin_amdgcn_s_barrier()
; #define PG8_SCHED __builtin_amdgcn_sched_barrier(0)
; template <class Epi>
; __device__ __forceinline__ void gemm_phase(LAS unsigned char* lds, const Gemm g, const StaticOrder& S, const Epi& E) {
;     ...
;             PG8_WAIT_V(6); PG8_BAR; PG8_MMA(1, 1, At, B1); PG8_BAR;
;             PG8_LDB(B0, 1, 0); PG8_SCHED; PG8_LDA(At, 1, 0); PG8_STAGE(PG8_SA(0, 1), a2 + hstepA, voffA);
;             PG8_WAIT_L(8); PG8_BAR; PG8_WAIT_L(0); PG8_MMA(0, 0, At, B0); PG8_BAR; PG8_SCHED;
;             PG8_LDB(B1, 1, 1); PG8_STAGE(PG8_SB(1, 0), b3, voffB);
;             PG8_BAR; PG8_WAIT_L(0); PG8_MMA(0, 1, At, B1); PG8_BAR;
;             PG8_LDA(At, 1, 1); PG8_STAGE(PG8_SA(1, 0), a3, voffA);
;             PG8_BAR; PG8_WAIT_L(0); PG8_MMA(1, 0, At, B0); PG8_BAR; PG8_SCHED;
	s_add_u32 s48, s22, 0x40000
	s_addc_u32 s49, s23, 0
	s_add_i32 s50, s39, s27
	v_lshl_add_u64 v[146:147], s[48:49], 0, v[132:133]
	s_mov_b32 m0, s50
	s_nop 0
	global_load_lds_dwordx4 v[146:147], off
	v_lshl_add_u64 v[146:147], s[48:49], 0, v[128:129]
	s_add_i32 m0, s50, 0x2000
	s_nop 0
	global_load_lds_dwordx4 v[146:147], off
	s_waitcnt vmcnt(6)
	s_barrier
	s_setprio 1
	v_mfma_f32_16x16x32_bf16 v[52:55], v[206:209], v[166:169], v[52:55]
	v_mfma_f32_16x16x32_bf16 v[44:47], v[214:217], v[166:169], v[44:47]
	v_mfma_f32_16x16x32_bf16 v[36:39], v[206:209], v[182:185], v[36:39]
	v_mfma_f32_16x16x32_bf16 v[28:31], v[214:217], v[182:185], v[28:31]
	v_mfma_f32_16x16x32_bf16 v[20:23], v[206:209], v[190:193], v[20:23]
	v_mfma_f32_16x16x32_bf16 v[12:15], v[214:217], v[190:193], v[12:15]
	v_mfma_f32_16x16x32_bf16 v[4:7], v[206:209], v[198:201], v[4:7]
	v_mfma_f32_16x16x32_bf16 v[0:3], v[214:217], v[198:201], v[0:3]
	v_mfma_f32_16x16x32_bf16 v[52:55], v[210:213], v[178:181], v[52:55]
	v_mfma_f32_16x16x32_bf16 v[44:47], v[218:221], v[178:181], v[44:47]
	v_mfma_f32_16x16x32_bf16 v[36:39], v[210:213], v[186:189], v[36:39]
	v_mfma_f32_16x16x32_bf16 v[28:31], v[218:221], v[186:189], v[28:31]
	v_mfma_f32_16x16x32_bf16 v[20:23], v[210:213], v[194:197], v[20:23]
	v_mfma_f32_16x16x32_bf16 v[12:15], v[218:221], v[194:197], v[12:15]
	v_mfma_f32_16x16x32_bf16 v[4:7], v[210:213], v[202:205], v[4:7]
	v_mfma_f32_16x16x32_bf16 v[0:3], v[218:221], v[202:205], v[0:3]
	s_setprio 0
	s_add_i32 s48, 0, 0x18000
	v_add_u32_e32 v162, s48, v171
	s_barrier
	ds_read_b128 v[146:149], v162
	ds_read_b128 v[154:157], v162 offset:1024
	ds_read_b128 v[158:161], v162 offset:2048
	ds_read_b128 v[162:165], v162 offset:3072
	s_add_u32 s24, s24, 0x40000
	s_addc_u32 s25, s25, 0
	s_mov_b32 m0, s31
	v_lshl_add_u64 v[206:207], s[24:25], 0, v[134:135]
	ds_read_b128 v[166:169], v174 offset:32768
	ds_read_b128 v[178:181], v174 offset:33792
	ds_read_b128 v[182:185], v174 offset:34816
	ds_read_b128 v[186:189], v174 offset:35840
	ds_read_b128 v[190:193], v174 offset:36864
	ds_read_b128 v[194:197], v174 offset:37888
	ds_read_b128 v[198:201], v174 offset:38912
	ds_read_b128 v[202:205], v174 offset:39936
	global_load_lds_dwordx4 v[206:207], off
	v_lshl_add_u64 v[206:207], s[24:25], 0, v[130:131]
	s_mov_b32 m0, s33
	s_nop 0
	global_load_lds_dwordx4 v[206:207], off
	s_waitcnt lgkmcnt(8)
	s_barrier
	s_waitcnt lgkmcnt(0)
	s_setprio 1
	s_waitcnt lgkmcnt(0)
	v_mfma_f32_16x16x32_bf16 v[124:127], v[146:149], v[166:169], v[124:127]
	v_mfma_f32_16x16x32_bf16 v[120:123], v[158:161], v[166:169], v[120:123]
	v_mfma_f32_16x16x32_bf16 v[112:115], v[146:149], v[182:185], v[112:115]
	v_mfma_f32_16x16x32_bf16 v[104:107], v[158:161], v[182:185], v[104:107]
	v_mfma_f32_16x16x32_bf16 v[92:95], v[146:149], v[190:193], v[92:95]
	v_mfma_f32_16x16x32_bf16 v[88:91], v[158:161], v[190:193], v[88:91]
	v_mfma_f32_16x16x32_bf16 v[80:83], v[146:149], v[198:201], v[80:83]
	v_mfma_f32_16x16x32_bf16 v[72:75], v[158:161], v[198:201], v[72:75]
	v_mfma_f32_16x16x32_bf16 v[124:127], v[154:157], v[178:181], v[124:127]
	v_mfma_f32_16x16x32_bf16 v[120:123], v[162:165], v[178:181], v[120:123]
	v_mfma_f32_16x16x32_bf16 v[112:115], v[154:157], v[186:189], v[112:115]
	v_mfma_f32_16x16x32_bf16 v[104:107], v[162:165], v[186:189], v[104:107]
	v_mfma_f32_16x16x32_bf16 v[92:95], v[154:157], v[194:197], v[92:95]
	v_mfma_f32_16x16x32_bf16 v[88:91], v[162:165], v[194:197], v[88:91]
	v_mfma_f32_16x16x32_bf16 v[80:83], v[154:157], v[202:205], v[80:83]
	v_mfma_f32_16x16x32_bf16 v[72:75], v[162:165], v[202:205], v[72:75]
	s_setprio 0
	s_barrier
	s_add_i32 s24, 0, 0x1c000
	s_add_i32 s25, s48, s27
	v_add_u32_e32 v177, s24, v171
	v_lshl_add_u64 v[150:151], v[150:151], 0, s[4:5]
	s_mov_b32 m0, s25
	ds_read_b128 v[206:209], v177
	ds_read_b128 v[210:213], v177 offset:1024
	ds_read_b128 v[214:217], v177 offset:2048
	ds_read_b128 v[218:221], v177 offset:3072
	global_load_lds_dwordx4 v[150:151], off
	v_lshl_add_u64 v[150:151], v[222:223], 0, s[4:5]
	s_add_i32 m0, s25, 0x2000
	s_nop 0
	global_load_lds_dwordx4 v[150:151], off
	s_barrier
	s_waitcnt lgkmcnt(0)
	s_setprio 1
	s_waitcnt lgkmcnt(0)
	v_mfma_f32_16x16x32_bf16 v[116:119], v[206:209], v[166:169], v[116:119]
	v_mfma_f32_16x16x32_bf16 v[108:111], v[214:217], v[166:169], v[108:111]
	v_mfma_f32_16x16x32_bf16 v[100:103], v[206:209], v[182:185], v[100:103]
	v_mfma_f32_16x16x32_bf16 v[96:99], v[214:217], v[182:185], v[96:99]
	v_mfma_f32_16x16x32_bf16 v[84:87], v[206:209], v[190:193], v[84:87]
	v_mfma_f32_16x16x32_bf16 v[76:79], v[214:217], v[190:193], v[76:79]
	v_mfma_f32_16x16x32_bf16 v[68:71], v[206:209], v[198:201], v[68:71]
	v_mfma_f32_16x16x32_bf16 v[64:67], v[214:217], v[198:201], v[64:67]
	v_mfma_f32_16x16x32_bf16 v[116:119], v[210:213], v[178:181], v[116:119]
	v_mfma_f32_16x16x32_bf16 v[108:111], v[218:221], v[178:181], v[108:111]
	v_mfma_f32_16x16x32_bf16 v[100:103], v[210:213], v[186:189], v[100:103]
	v_mfma_f32_16x16x32_bf16 v[96:99], v[218:221], v[186:189], v[96:99]
	v_mfma_f32_16x16x32_bf16 v[84:87], v[210:213], v[194:197], v[84:87]
	v_mfma_f32_16x16x32_bf16 v[76:79], v[218:221], v[194:197], v[76:79]
	v_mfma_f32_16x16x32_bf16 v[68:71], v[210:213], v[202:205], v[68:71]
	v_mfma_f32_16x16x32_bf16 v[64:67], v[218:221], v[202:205], v[64:67]
	s_setprio 0
	s_mov_b32 m0, s35
	v_lshl_add_u64 v[150:151], v[224:225], 0, s[4:5]
	s_barrier
	ds_read_b128 v[166:169], v174 offset:49152
	ds_read_b128 v[178:181], v174 offset:50176
	ds_read_b128 v[182:185], v174 offset:51200
	ds_read_b128 v[186:189], v174 offset:52224
	ds_read_b128 v[190:193], v174 offset:53248
	ds_read_b128 v[194:197], v174 offset:54272
	ds_read_b128 v[198:201], v174 offset:55296
	ds_read_b128 v[202:205], v174 offset:56320
	global_load_lds_dwordx4 v[150:151], off
	v_lshl_add_u64 v[150:151], v[226:227], 0, s[4:5]
	s_mov_b32 m0, s36
	s_nop 0
	global_load_lds_dwordx4 v[150:151], off
	s_barrier
; __device__ __forceinline__ unsigned pk2(float lo, float hi) { const f32x2 v = (f32x2){lo, hi}; const bf16x2_t b = __builtin_convertvector(v, bf16x2_t); return __builtin_bit_cast(unsigned, b); }
; #define PG8_STAGE(bufoff, gbase, voff) do { _Pragma("unroll") for (int _i = 0; _i < 2; ++_i) \
;         __builtin_amdgcn_global_load_lds((const unsigned*)((const char*)(gbase) + (voff)[_i]), (LAS unsigned*)(lds + (bufoff) + ldsw + _i * 8192), 16, 0, 0); } while (0)
; #define PG8_MMA(ai, bj, At, Bt) do { __builtin_amdgcn_s_setprio(1); _Pragma("unroll") for (int m = 0; m < 4; ++m) _Pragma("unroll") for (int n = 0; n < 2; ++n) _Pragma("unroll") for (int k = 0; k < 2; ++k) \
;         acc[ai][bj][m][n] = __builtin_amdgcn_mfma_f32_16x16x32_bf16(Bt[n][k], At[m][k], acc[ai][bj][m][n], 0, 0, 0); __builtin_amdgcn_s_setprio(0); } while (0)
; #define PG8_WAIT_V(n) asm volatile("s_waitcnt vmcnt(" #n ")" ::: "memory")
; #define PG8_WAIT_L(n) asm volatile("s_waitcnt lgkmcnt(" #n ")" ::: "memory")
;     __device__ __forceinline__ void operator()(const f32x4 (&acc)[2][2][4][2], const Unit& u, int wr, int wc, int fr, int fq, const float (&)[8]) const {
;     ...
;         const int col0 = u.pn * BM + wc * 32 + 8 * fq;
; #pragma unroll
;         for (int ai = 0; ai < 2; ++ai)
; #pragma unroll
;             for (int m = 0; m < 4; ++m) { const int row = row0 + ai * HALF + m * 16; const float rs = rsqrtf(ep[ai * 4 + m] * (1.0f / 1024.0f) + EPS);
;                 u16* rowp = O + (size_t)row * ldc + col0;
; #pragma unroll
;                 for (int bj = 0; bj < 2; ++bj) { f32x4 v0 = acc[ai][bj][m][0] * rs, v1 = acc[ai][bj][m][1] * rs;
;                     if (ACT == 1) {
; #pragma unroll
;                         for (int j = 0; j < 4; ++j) { const float a0 = fmaxf(v0[j], 0.f), a1 = fmaxf(v1[j], 0.f); v0[j] = a0 * a0; v1[j] = a1 * a1; } }
;                     u32x4 w; w.x = pk2(v0[0], v0[1]); w.y = pk2(v0[2], v0[3]); w.z = pk2(v1[0], v1[1]); w.w = pk2(v1[2], v1[3]);
;                     *(u32x4*)(rowp + bj * HALF) = w; } }
; template <class Epi>
; __device__ __forceinline__ void gemm_phase(LAS unsigned char* lds, const Gemm g, const StaticOrder& S, const Epi& E) {
;     ...
;             PG8_BAR; PG8_WAIT_L(0); PG8_MMA(1, 0, At, B0); PG8_BAR; PG8_SCHED;
;             PG8_STAGE(PG8_SB(1, 1), b3 + hstepB, voffB);
;             PG8_WAIT_V(6); PG8_BAR; PG8_MMA(1, 1, At, B1); PG8_BAR;
	s_waitcnt lgkmcnt(0)
	s_setprio 1
	s_waitcnt lgkmcnt(0)
	v_mfma_f32_16x16x32_bf16 v[60:63], v[146:149], v[166:169], v[60:63]
	v_mfma_f32_16x16x32_bf16 v[56:59], v[158:161], v[166:169], v[56:59]
	v_mfma_f32_16x16x32_bf16 v[48:51], v[146:149], v[182:185], v[48:51]
	v_mfma_f32_16x16x32_bf16 v[40:43], v[158:161], v[182:185], v[40:43]
	v_mfma_f32_16x16x32_bf16 v[32:35], v[146:149], v[190:193], v[32:35]
	v_mfma_f32_16x16x32_bf16 v[24:27], v[158:161], v[190:193], v[24:27]
	v_mfma_f32_16x16x32_bf16 v[16:19], v[146:149], v[198:201], v[16:19]
	v_mfma_f32_16x16x32_bf16 v[8:11], v[158:161], v[198:201], v[8:11]
	v_mfma_f32_16x16x32_bf16 v[60:63], v[154:157], v[178:181], v[60:63]
	v_mfma_f32_16x16x32_bf16 v[56:59], v[162:165], v[178:181], v[56:59]
	v_mfma_f32_16x16x32_bf16 v[48:51], v[154:157], v[186:189], v[48:51]
	v_mfma_f32_16x16x32_bf16 v[40:43], v[162:165], v[186:189], v[40:43]
	v_mfma_f32_16x16x32_bf16 v[32:35], v[154:157], v[194:197], v[32:35]
	v_mfma_f32_16x16x32_bf16 v[24:27], v[162:165], v[194:197], v[24:27]
	v_mfma_f32_16x16x32_bf16 v[16:19], v[154:157], v[202:205], v[16:19]
	v_mfma_f32_16x16x32_bf16 v[8:11], v[162:165], v[202:205], v[8:11]
	s_setprio 0
	s_barrier
	s_add_u32 s22, s22, 0x40080
	s_addc_u32 s23, s23, 0
	s_add_i32 s24, s24, s27
	v_lshl_add_u64 v[146:147], s[22:23], 0, v[132:133]
	s_mov_b32 m0, s24
	s_nop 0
	global_load_lds_dwordx4 v[146:147], off
	v_lshl_add_u64 v[146:147], s[22:23], 0, v[128:129]
	s_add_i32 m0, s24, 0x2000
	s_nop 0
	global_load_lds_dwordx4 v[146:147], off
	s_waitcnt vmcnt(6)
	s_barrier
	s_setprio 1
	v_mfma_f32_16x16x32_bf16 v[52:55], v[206:209], v[166:169], v[52:55]
	v_mfma_f32_16x16x32_bf16 v[44:47], v[214:217], v[166:169], v[44:47]
	v_mfma_f32_16x16x32_bf16 v[36:39], v[206:209], v[182:185], v[36:39]
	v_mfma_f32_16x16x32_bf16 v[28:31], v[214:217], v[182:185], v[28:31]
	v_mfma_f32_16x16x32_bf16 v[20:23], v[206:209], v[190:193], v[20:23]
	v_mfma_f32_16x16x32_bf16 v[12:15], v[214:217], v[190:193], v[12:15]
	v_mfma_f32_16x16x32_bf16 v[4:7], v[206:209], v[198:201], v[4:7]
	v_mfma_f32_16x16x32_bf16 v[0:3], v[214:217], v[198:201], v[0:3]
	v_mfma_f32_16x16x32_bf16 v[52:55], v[210:213], v[178:181], v[52:55]
	v_mfma_f32_16x16x32_bf16 v[44:47], v[218:221], v[178:181], v[44:47]
	v_mfma_f32_16x16x32_bf16 v[36:39], v[210:213], v[186:189], v[36:39]
	v_mfma_f32_16x16x32_bf16 v[28:31], v[218:221], v[186:189], v[28:31]
	v_mfma_f32_16x16x32_bf16 v[20:23], v[210:213], v[194:197], v[20:23]
	v_mfma_f32_16x16x32_bf16 v[12:15], v[218:221], v[194:197], v[12:15]
	v_mfma_f32_16x16x32_bf16 v[4:7], v[210:213], v[202:205], v[4:7]
	v_mfma_f32_16x16x32_bf16 v[0:3], v[218:221], v[202:205], v[0:3]
	s_setprio 0
	s_add_i32 s47, s47, 2
	s_add_u32 s20, s20, 0x100
	s_addc_u32 s21, s21, 0
	s_add_u32 s45, s45, 0x100
	s_addc_u32 s46, s46, 0
	s_cmp_gt_u32 s47, 13
	s_barrier
	s_cbranch_scc0 .LBB0_922
	s_bfe_u32 vcc_lo, s18, 0x20003
	s_lshl_b32 vcc_lo, vcc_lo, 10
	s_add_i32 vcc_lo, vcc_lo, 0x20010
	v_lshl_add_u32 v236, v170, 2, vcc_lo
	ds_read_b32 v228, v236
	ds_read_b32 v229, v236 offset:64
	ds_read_b32 v230, v236 offset:128
	ds_read_b32 v231, v236 offset:192
	ds_read_b32 v232, v236 offset:512
	ds_read_b32 v233, v236 offset:576
	ds_read_b32 v234, v236 offset:640
	ds_read_b32 v235, v236 offset:704
	s_waitcnt lgkmcnt(0)
	v_lshl_add_u32 v154, s18, 8, v170
	v_and_b32_e32 v236, 8, v170
	v_sub_u32_e32 v154, v154, v236
	s_mov_b32 vcc_lo, 0x14000
	s_mov_b32 vcc_hi, 0
	v_or_b32_e32 v206, 16, v154
	v_or_b32_e32 v168, 32, v154
	v_or_b32_e32 v162, 48, v154
	v_add_u32_e32 v160, 0x80, v154
	v_add_u32_e32 v156, 0x90, v154
	v_add_u32_e32 v150, 0xa0, v154
	v_add_u32_e32 v146, 0xb0, v154
	v_and_b32_e32 v237, 0x60, v172
	v_lshlrev_b32_e32 v237, 1, v237
	v_and_b32_e32 v238, 0x18, v172
	v_or_b32_e32 v237, v237, v238
	v_lshl_or_b32 v237, v236, 2, v237
	v_lshl_or_b32 v208, s42, 8, v237
	v_mov_b64_e32 v[148:149], s[96:97]
	v_ashrrev_i32_e32 v209, 31, v208
	v_mad_i64_i32 v[210:211], s[20:21], v154, s40, v[148:149]
	s_nop 0
	v_lshlrev_b64 v[154:155], 1, v[208:209]
	v_lshl_add_u64 v[208:209], v[210:211], 0, v[154:155]
	s_mov_b32 s42, s10
	s_mov_b32 s18, s12
	s_mov_b64 s[22:23], s[16:17]
	s_waitcnt vmcnt(8)
	s_waitcnt lgkmcnt(0)
	s_waitcnt lgkmcnt(0)
	v_mov_b32_e32 v178, v228
	v_pk_mul_f32 v[126:127], v[126:127], v[178:179] op_sel_hi:[1,0]
	v_pk_mul_f32 v[124:125], v[124:125], v[178:179] op_sel_hi:[1,0]
	v_pk_mul_f32 v[190:191], v[122:123], v[178:179] op_sel_hi:[1,0]
	v_pk_mul_f32 v[122:123], v[120:121], v[178:179] op_sel_hi:[1,0]
	v_cvt_pk_bf16_f32 v238, v124, v125
	v_cvt_pk_bf16_f32 v239, v126, v127
	v_cvt_pk_bf16_f32 v240, v122, v123
	v_cvt_pk_bf16_f32 v241, v190, v191
	v_pk_mul_f32 v[116:117], v[116:117], v[178:179] op_sel_hi:[1,0]
	s_nop 0
	v_pk_mul_f32 v[118:119], v[118:119], v[178:179] op_sel_hi:[1,0]
	v_pk_mul_f32 v[120:121], v[110:111], v[178:179] op_sel_hi:[1,0]
	v_pk_mul_f32 v[110:111], v[108:109], v[178:179] op_sel_hi:[1,0]
	v_cvt_pk_bf16_f32 v242, v116, v117
	v_cvt_pk_bf16_f32 v243, v118, v119
	v_cvt_pk_bf16_f32 v244, v110, v111
	v_cvt_pk_bf16_f32 v245, v120, v121
	v_mov_b32_e32 v246, v238
	v_mov_b32_e32 v247, v239
	v_mov_b32_e32 v248, v240
	v_mov_b32_e32 v249, v241
	v_mov_b32_dpp v238, v242 row_shr:8 row_mask:0xf bank_mask:0xc
	v_mov_b32_dpp v239, v243 row_shr:8 row_mask:0xf bank_mask:0xc
	v_mov_b32_dpp v240, v244 row_shr:8 row_mask:0xf bank_mask:0xc
	v_mov_b32_dpp v241, v245 row_shr:8 row_mask:0xf bank_mask:0xc
	global_store_dwordx4 v[208:209], v[238:241], off
	v_lshl_add_u64 v[236:237], v[208:209], 0, vcc
	v_mov_b32_dpp v242, v246 row_shl:8 row_mask:0xf bank_mask:0x3
	v_mov_b32_dpp v243, v247 row_shl:8 row_mask:0xf bank_mask:0x3
	v_mov_b32_dpp v244, v248 row_shl:8 row_mask:0xf bank_mask:0x3
	v_mov_b32_dpp v245, v249 row_shl:8 row_mask:0xf bank_mask:0x3
	global_store_dwordx4 v[236:237], v[242:245], off
	s_nop 1
	v_mov_b32_e32 v108, v229
	v_mad_i64_i32 v[110:111], s[20:21], v206, s40, v[148:149]
	v_pk_mul_f32 v[114:115], v[114:115], v[108:109] op_sel_hi:[1,0]
	v_pk_mul_f32 v[112:113], v[112:113], v[108:109] op_sel_hi:[1,0]
	v_pk_mul_f32 v[116:117], v[106:107], v[108:109] op_sel_hi:[1,0]
	v_pk_mul_f32 v[106:107], v[104:105], v[108:109] op_sel_hi:[1,0]
	v_lshl_add_u64 v[110:111], v[110:111], 0, v[154:155]
	v_cvt_pk_bf16_f32 v238, v112, v113
	v_cvt_pk_bf16_f32 v239, v114, v115
	v_cvt_pk_bf16_f32 v240, v106, v107
	v_cvt_pk_bf16_f32 v241, v116, v117
	v_pk_mul_f32 v[100:101], v[100:101], v[108:109] op_sel_hi:[1,0]
	v_pk_mul_f32 v[112:113], v[98:99], v[108:109] op_sel_hi:[1,0]
	v_pk_mul_f32 v[98:99], v[96:97], v[108:109] op_sel_hi:[1,0]
	v_cvt_pk_bf16_f32 v242, v100, v101
	v_pk_mul_f32 v[102:103], v[102:103], v[108:109] op_sel_hi:[1,0]
	v_cvt_pk_bf16_f32 v244, v98, v99
	s_waitcnt lgkmcnt(0)
; __device__ __forceinline__ unsigned pk2(float lo, float hi) { const f32x2 v = (f32x2){lo, hi}; const bf16x2_t b = __builtin_convertvector(v, bf16x2_t); return __builtin_bit_cast(unsigned, b); }
;     __device__ __forceinline__ void operator()(const f32x4 (&acc)[2][2][4][2], const Unit& u, int wr, int wc, int fr, int fq, const float (&)[8]) const {
;     ...
;         const int col0 = u.pn * BM + wc * 32 + 8 * fq;
; #pragma unroll
;         for (int ai = 0; ai < 2; ++ai)
; #pragma unroll
;             for (int m = 0; m < 4; ++m) { const int row = row0 + ai * HALF + m * 16; const float rs = rsqrtf(ep[ai * 4 + m] * (1.0f / 1024.0f) + EPS);
;                 u16* rowp = O + (size_t)row * ldc + col0;
; #pragma unroll
;                 for (int bj = 0; bj < 2; ++bj) { f32x4 v0 = acc[ai][bj][m][0] * rs, v1 = acc[ai][bj][m][1] * rs;
;                     if (ACT == 1) {
; #pragma unroll
;                         for (int j = 0; j < 4; ++j) { const float a0 = fmaxf(v0[j], 0.f), a1 = fmaxf(v1[j], 0.f); v0[j] = a0 * a0; v1[j] = a1 * a1; } }
;                     u32x4 w; w.x = pk2(v0[0], v0[1]); w.y = pk2(v0[2], v0[3]); w.z = pk2(v1[0], v1[1]); w.w = pk2(v1[2], v1[3]);
;                     *(u32x4*)(rowp + bj * HALF) = w; } }
	v_cvt_pk_bf16_f32 v243, v102, v103
	v_cvt_pk_bf16_f32 v245, v112, v113
	v_mov_b32_e32 v246, v238
	v_mov_b32_e32 v247, v239
	v_mov_b32_e32 v248, v240
	v_mov_b32_e32 v249, v241
	v_mov_b32_dpp v238, v242 row_shr:8 row_mask:0xf bank_mask:0xc
	v_mov_b32_dpp v239, v243 row_shr:8 row_mask:0xf bank_mask:0xc
	v_mov_b32_dpp v240, v244 row_shr:8 row_mask:0xf bank_mask:0xc
	v_mov_b32_dpp v241, v245 row_shr:8 row_mask:0xf bank_mask:0xc
	global_store_dwordx4 v[110:111], v[238:241], off
	v_lshl_add_u64 v[236:237], v[110:111], 0, vcc
	v_mov_b32_dpp v242, v246 row_shl:8 row_mask:0xf bank_mask:0x3
	v_mov_b32_dpp v243, v247 row_shl:8 row_mask:0xf bank_mask:0x3
	v_mov_b32_dpp v244, v248 row_shl:8 row_mask:0xf bank_mask:0x3
	v_mov_b32_dpp v245, v249 row_shl:8 row_mask:0xf bank_mask:0x3
	global_store_dwordx4 v[236:237], v[242:245], off
	s_nop 0
	s_waitcnt lgkmcnt(0)
	v_mad_i64_i32 v[98:99], s[20:21], v168, s40, v[148:149]
	v_lshl_add_u64 v[98:99], v[98:99], 0, v[154:155]
	v_mov_b32_e32 v100, v230
	v_pk_mul_f32 v[94:95], v[94:95], v[100:101] op_sel_hi:[1,0]
	v_pk_mul_f32 v[92:93], v[92:93], v[100:101] op_sel_hi:[1,0]
	v_pk_mul_f32 v[102:103], v[90:91], v[100:101] op_sel_hi:[1,0]
	v_pk_mul_f32 v[90:91], v[88:89], v[100:101] op_sel_hi:[1,0]
	v_cvt_pk_bf16_f32 v238, v92, v93
	v_cvt_pk_bf16_f32 v239, v94, v95
	v_cvt_pk_bf16_f32 v240, v90, v91
	v_cvt_pk_bf16_f32 v241, v102, v103
	v_pk_mul_f32 v[84:85], v[84:85], v[100:101] op_sel_hi:[1,0]
	s_nop 0
	v_pk_mul_f32 v[86:87], v[86:87], v[100:101] op_sel_hi:[1,0]
	v_pk_mul_f32 v[88:89], v[78:79], v[100:101] op_sel_hi:[1,0]
	v_pk_mul_f32 v[78:79], v[76:77], v[100:101] op_sel_hi:[1,0]
	v_cvt_pk_bf16_f32 v242, v84, v85
	v_cvt_pk_bf16_f32 v243, v86, v87
	v_cvt_pk_bf16_f32 v244, v78, v79
	v_cvt_pk_bf16_f32 v245, v88, v89
	v_mov_b32_e32 v246, v238
	v_mov_b32_e32 v247, v239
	v_mov_b32_e32 v248, v240
	v_mov_b32_e32 v249, v241
	v_mov_b32_dpp v238, v242 row_shr:8 row_mask:0xf bank_mask:0xc
	v_mov_b32_dpp v239, v243 row_shr:8 row_mask:0xf bank_mask:0xc
	v_mov_b32_dpp v240, v244 row_shr:8 row_mask:0xf bank_mask:0xc
	v_mov_b32_dpp v241, v245 row_shr:8 row_mask:0xf bank_mask:0xc
	global_store_dwordx4 v[98:99], v[238:241], off
	v_lshl_add_u64 v[236:237], v[98:99], 0, vcc
	v_mov_b32_dpp v242, v246 row_shl:8 row_mask:0xf bank_mask:0x3
	v_mov_b32_dpp v243, v247 row_shl:8 row_mask:0xf bank_mask:0x3
	v_mov_b32_dpp v244, v248 row_shl:8 row_mask:0xf bank_mask:0x3
	v_mov_b32_dpp v245, v249 row_shl:8 row_mask:0xf bank_mask:0x3
	global_store_dwordx4 v[236:237], v[242:245], off
	s_nop 1
	v_mov_b32_e32 v76, v231
	v_mad_i64_i32 v[78:79], s[20:21], v162, s40, v[148:149]
	v_pk_mul_f32 v[82:83], v[82:83], v[76:77] op_sel_hi:[1,0]
	v_pk_mul_f32 v[80:81], v[80:81], v[76:77] op_sel_hi:[1,0]
	v_pk_mul_f32 v[84:85], v[74:75], v[76:77] op_sel_hi:[1,0]
	v_pk_mul_f32 v[74:75], v[72:73], v[76:77] op_sel_hi:[1,0]
	v_lshl_add_u64 v[78:79], v[78:79], 0, v[154:155]
	v_cvt_pk_bf16_f32 v238, v80, v81
	v_cvt_pk_bf16_f32 v239, v82, v83
	v_cvt_pk_bf16_f32 v240, v74, v75
	v_cvt_pk_bf16_f32 v241, v84, v85
	v_pk_mul_f32 v[68:69], v[68:69], v[76:77] op_sel_hi:[1,0]
	v_pk_mul_f32 v[80:81], v[66:67], v[76:77] op_sel_hi:[1,0]
	v_pk_mul_f32 v[66:67], v[64:65], v[76:77] op_sel_hi:[1,0]
	v_cvt_pk_bf16_f32 v242, v68, v69
	v_pk_mul_f32 v[70:71], v[70:71], v[76:77] op_sel_hi:[1,0]
	v_cvt_pk_bf16_f32 v244, v66, v67
	s_waitcnt lgkmcnt(0)
	v_cvt_pk_bf16_f32 v243, v70, v71
	v_cvt_pk_bf16_f32 v245, v80, v81
	v_mov_b32_e32 v246, v238
	v_mov_b32_e32 v247, v239
	v_mov_b32_e32 v248, v240
	v_mov_b32_e32 v249, v241
	v_mov_b32_dpp v238, v242 row_shr:8 row_mask:0xf bank_mask:0xc
	v_mov_b32_dpp v239, v243 row_shr:8 row_mask:0xf bank_mask:0xc
	v_mov_b32_dpp v240, v244 row_shr:8 row_mask:0xf bank_mask:0xc
	v_mov_b32_dpp v241, v245 row_shr:8 row_mask:0xf bank_mask:0xc
	global_store_dwordx4 v[78:79], v[238:241], off
	v_lshl_add_u64 v[236:237], v[78:79], 0, vcc
	v_mov_b32_dpp v242, v246 row_shl:8 row_mask:0xf bank_mask:0x3
	v_mov_b32_dpp v243, v247 row_shl:8 row_mask:0xf bank_mask:0x3
	v_mov_b32_dpp v244, v248 row_shl:8 row_mask:0xf bank_mask:0x3
	v_mov_b32_dpp v245, v249 row_shl:8 row_mask:0xf bank_mask:0x3
	global_store_dwordx4 v[236:237], v[242:245], off
	s_waitcnt lgkmcnt(0)
	s_nop 0
	s_nop 0
	s_nop 0
	s_nop 1
	v_mad_i64_i32 v[66:67], s[20:21], v160, s40, v[148:149]
	v_lshl_add_u64 v[66:67], v[66:67], 0, v[154:155]
	v_mov_b32_e32 v68, v232
	v_pk_mul_f32 v[62:63], v[62:63], v[68:69] op_sel_hi:[1,0]
	v_pk_mul_f32 v[60:61], v[60:61], v[68:69] op_sel_hi:[1,0]
	v_pk_mul_f32 v[70:71], v[58:59], v[68:69] op_sel_hi:[1,0]
	v_pk_mul_f32 v[58:59], v[56:57], v[68:69] op_sel_hi:[1,0]
	v_cvt_pk_bf16_f32 v238, v60, v61
	v_cvt_pk_bf16_f32 v239, v62, v63
	v_cvt_pk_bf16_f32 v240, v58, v59
	v_cvt_pk_bf16_f32 v241, v70, v71
	v_pk_mul_f32 v[52:53], v[52:53], v[68:69] op_sel_hi:[1,0]
	s_nop 0
	v_pk_mul_f32 v[54:55], v[54:55], v[68:69] op_sel_hi:[1,0]
	v_pk_mul_f32 v[56:57], v[46:47], v[68:69] op_sel_hi:[1,0]
	v_pk_mul_f32 v[46:47], v[44:45], v[68:69] op_sel_hi:[1,0]
	v_cvt_pk_bf16_f32 v242, v52, v53
	v_cvt_pk_bf16_f32 v243, v54, v55
	v_cvt_pk_bf16_f32 v244, v46, v47
	v_cvt_pk_bf16_f32 v245, v56, v57
	v_mov_b32_e32 v246, v238
	v_mov_b32_e32 v247, v239
	v_mov_b32_e32 v248, v240
	v_mov_b32_e32 v249, v241
	v_mov_b32_dpp v238, v242 row_shr:8 row_mask:0xf bank_mask:0xc
	v_mov_b32_dpp v239, v243 row_shr:8 row_mask:0xf bank_mask:0xc
	v_mov_b32_dpp v240, v244 row_shr:8 row_mask:0xf bank_mask:0xc
	v_mov_b32_dpp v241, v245 row_shr:8 row_mask:0xf bank_mask:0xc
	global_store_dwordx4 v[66:67], v[238:241], off
	v_lshl_add_u64 v[236:237], v[66:67], 0, vcc
	v_mov_b32_dpp v242, v246 row_shl:8 row_mask:0xf bank_mask:0x3
	v_mov_b32_dpp v243, v247 row_shl:8 row_mask:0xf bank_mask:0x3
	v_mov_b32_dpp v244, v248 row_shl:8 row_mask:0xf bank_mask:0x3
	v_mov_b32_dpp v245, v249 row_shl:8 row_mask:0xf bank_mask:0x3
	global_store_dwordx4 v[236:237], v[242:245], off
	s_nop 1
	v_mov_b32_e32 v44, v233
	v_mad_i64_i32 v[46:47], s[20:21], v156, s40, v[148:149]
	v_pk_mul_f32 v[50:51], v[50:51], v[44:45] op_sel_hi:[1,0]
	v_pk_mul_f32 v[48:49], v[48:49], v[44:45] op_sel_hi:[1,0]
	v_pk_mul_f32 v[52:53], v[42:43], v[44:45] op_sel_hi:[1,0]
	v_pk_mul_f32 v[42:43], v[40:41], v[44:45] op_sel_hi:[1,0]
	v_lshl_add_u64 v[46:47], v[46:47], 0, v[154:155]
	v_cvt_pk_bf16_f32 v238, v48, v49
	v_cvt_pk_bf16_f32 v239, v50, v51
	v_cvt_pk_bf16_f32 v240, v42, v43
	v_cvt_pk_bf16_f32 v241, v52, v53
	v_pk_mul_f32 v[36:37], v[36:37], v[44:45] op_sel_hi:[1,0]
	v_pk_mul_f32 v[48:49], v[30:31], v[44:45] op_sel_hi:[1,0]
	v_pk_mul_f32 v[30:31], v[28:29], v[44:45] op_sel_hi:[1,0]
	v_cvt_pk_bf16_f32 v242, v36, v37
	v_pk_mul_f32 v[38:39], v[38:39], v[44:45] op_sel_hi:[1,0]
	v_cvt_pk_bf16_f32 v244, v30, v31
	s_waitcnt lgkmcnt(0)
; __device__ __forceinline__ unsigned pk2(float lo, float hi) { const f32x2 v = (f32x2){lo, hi}; const bf16x2_t b = __builtin_convertvector(v, bf16x2_t); return __builtin_bit_cast(unsigned, b); }
;     __device__ __forceinline__ void operator()(const f32x4 (&acc)[2][2][4][2], const Unit& u, int wr, int wc, int fr, int fq, const float (&)[8]) const {
;     ...
;         const int col0 = u.pn * BM + wc * 32 + 8 * fq;
; #pragma unroll
;         for (int ai = 0; ai < 2; ++ai)
; #pragma unroll
;             for (int m = 0; m < 4; ++m) { const int row = row0 + ai * HALF + m * 16; const float rs = rsqrtf(ep[ai * 4 + m] * (1.0f / 1024.0f) + EPS);
;                 u16* rowp = O + (size_t)row * ldc + col0;
; #pragma unroll
;                 for (int bj = 0; bj < 2; ++bj) { f32x4 v0 = acc[ai][bj][m][0] * rs, v1 = acc[ai][bj][m][1] * rs;
;                     if (ACT == 1) {
; #pragma unroll
;                         for (int j = 0; j < 4; ++j) { const float a0 = fmaxf(v0[j], 0.f), a1 = fmaxf(v1[j], 0.f); v0[j] = a0 * a0; v1[j] = a1 * a1; } }
;                     u32x4 w; w.x = pk2(v0[0], v0[1]); w.y = pk2(v0[2], v0[3]); w.z = pk2(v1[0], v1[1]); w.w = pk2(v1[2], v1[3]);
;                     *(u32x4*)(rowp + bj * HALF) = w; } }
; template <class Epi>
; __device__ __forceinline__ void gemm_phase(LAS unsigned char* lds, const Gemm g, const StaticOrder& S, const Epi& E) {
;     ...
;         E(acc, cur, wr, wc, fr, fq, epre);
;         if (!has_next) break;
	v_cvt_pk_bf16_f32 v243, v38, v39
	v_cvt_pk_bf16_f32 v245, v48, v49
	v_mov_b32_e32 v246, v238
	v_mov_b32_e32 v247, v239
	v_mov_b32_e32 v248, v240
	v_mov_b32_e32 v249, v241
	v_mov_b32_dpp v238, v242 row_shr:8 row_mask:0xf bank_mask:0xc
	v_mov_b32_dpp v239, v243 row_shr:8 row_mask:0xf bank_mask:0xc
	v_mov_b32_dpp v240, v244 row_shr:8 row_mask:0xf bank_mask:0xc
	v_mov_b32_dpp v241, v245 row_shr:8 row_mask:0xf bank_mask:0xc
	global_store_dwordx4 v[46:47], v[238:241], off
	v_lshl_add_u64 v[236:237], v[46:47], 0, vcc
	v_mov_b32_dpp v242, v246 row_shl:8 row_mask:0xf bank_mask:0x3
	v_mov_b32_dpp v243, v247 row_shl:8 row_mask:0xf bank_mask:0x3
	v_mov_b32_dpp v244, v248 row_shl:8 row_mask:0xf bank_mask:0x3
	v_mov_b32_dpp v245, v249 row_shl:8 row_mask:0xf bank_mask:0x3
	global_store_dwordx4 v[236:237], v[242:245], off
	s_waitcnt lgkmcnt(0)
	s_nop 0
	s_nop 0
	s_nop 0
	s_nop 1
	v_mad_i64_i32 v[30:31], s[20:21], v150, s40, v[148:149]
	v_lshl_add_u64 v[30:31], v[30:31], 0, v[154:155]
	v_mov_b32_e32 v36, v234
	v_pk_mul_f32 v[34:35], v[34:35], v[36:37] op_sel_hi:[1,0]
	v_pk_mul_f32 v[32:33], v[32:33], v[36:37] op_sel_hi:[1,0]
	v_pk_mul_f32 v[38:39], v[26:27], v[36:37] op_sel_hi:[1,0]
	v_pk_mul_f32 v[26:27], v[24:25], v[36:37] op_sel_hi:[1,0]
	v_cvt_pk_bf16_f32 v238, v32, v33
	v_cvt_pk_bf16_f32 v239, v34, v35
	v_cvt_pk_bf16_f32 v240, v26, v27
	v_cvt_pk_bf16_f32 v241, v38, v39
	v_pk_mul_f32 v[20:21], v[20:21], v[36:37] op_sel_hi:[1,0]
	s_nop 0
	v_pk_mul_f32 v[22:23], v[22:23], v[36:37] op_sel_hi:[1,0]
	v_pk_mul_f32 v[24:25], v[14:15], v[36:37] op_sel_hi:[1,0]
	v_pk_mul_f32 v[14:15], v[12:13], v[36:37] op_sel_hi:[1,0]
	v_cvt_pk_bf16_f32 v242, v20, v21
	v_cvt_pk_bf16_f32 v243, v22, v23
	v_cvt_pk_bf16_f32 v244, v14, v15
	v_cvt_pk_bf16_f32 v245, v24, v25
	v_mov_b32_e32 v246, v238
	v_mov_b32_e32 v247, v239
	v_mov_b32_e32 v248, v240
	v_mov_b32_e32 v249, v241
	v_mov_b32_dpp v238, v242 row_shr:8 row_mask:0xf bank_mask:0xc
	v_mov_b32_dpp v239, v243 row_shr:8 row_mask:0xf bank_mask:0xc
	v_mov_b32_dpp v240, v244 row_shr:8 row_mask:0xf bank_mask:0xc
	v_mov_b32_dpp v241, v245 row_shr:8 row_mask:0xf bank_mask:0xc
	global_store_dwordx4 v[30:31], v[238:241], off
	v_lshl_add_u64 v[236:237], v[30:31], 0, vcc
	v_mov_b32_dpp v242, v246 row_shl:8 row_mask:0xf bank_mask:0x3
	v_mov_b32_dpp v243, v247 row_shl:8 row_mask:0xf bank_mask:0x3
	v_mov_b32_dpp v244, v248 row_shl:8 row_mask:0xf bank_mask:0x3
	v_mov_b32_dpp v245, v249 row_shl:8 row_mask:0xf bank_mask:0x3
	global_store_dwordx4 v[236:237], v[242:245], off
	s_nop 1
	v_mov_b32_e32 v12, v235
	v_mad_i64_i32 v[14:15], s[20:21], v146, s40, v[148:149]
	v_pk_mul_f32 v[18:19], v[18:19], v[12:13] op_sel_hi:[1,0]
	v_pk_mul_f32 v[16:17], v[16:17], v[12:13] op_sel_hi:[1,0]
	v_pk_mul_f32 v[20:21], v[10:11], v[12:13] op_sel_hi:[1,0]
	v_pk_mul_f32 v[10:11], v[8:9], v[12:13] op_sel_hi:[1,0]
	v_lshl_add_u64 v[14:15], v[14:15], 0, v[154:155]
	v_cvt_pk_bf16_f32 v238, v16, v17
	v_cvt_pk_bf16_f32 v239, v18, v19
	v_cvt_pk_bf16_f32 v240, v10, v11
	v_cvt_pk_bf16_f32 v241, v20, v21
	v_pk_mul_f32 v[6:7], v[6:7], v[12:13] op_sel_hi:[1,0]
	v_pk_mul_f32 v[4:5], v[4:5], v[12:13] op_sel_hi:[1,0]
	v_pk_mul_f32 v[8:9], v[2:3], v[12:13] op_sel_hi:[1,0]
	v_pk_mul_f32 v[2:3], v[0:1], v[12:13] op_sel_hi:[1,0]
	v_cvt_pk_bf16_f32 v242, v4, v5
	v_cvt_pk_bf16_f32 v243, v6, v7
	v_cvt_pk_bf16_f32 v244, v2, v3
	v_cvt_pk_bf16_f32 v245, v8, v9
	s_mov_b64 s[20:21], s[14:15]
	v_mov_b32_e32 v246, v238
	v_mov_b32_e32 v247, v239
	v_mov_b32_e32 v248, v240
	v_mov_b32_e32 v249, v241
	v_mov_b32_dpp v238, v242 row_shr:8 row_mask:0xf bank_mask:0xc
	v_mov_b32_dpp v239, v243 row_shr:8 row_mask:0xf bank_mask:0xc
	v_mov_b32_dpp v240, v244 row_shr:8 row_mask:0xf bank_mask:0xc
	v_mov_b32_dpp v241, v245 row_shr:8 row_mask:0xf bank_mask:0xc
	global_store_dwordx4 v[14:15], v[238:241], off
	v_lshl_add_u64 v[236:237], v[14:15], 0, vcc
	v_mov_b32_dpp v242, v246 row_shl:8 row_mask:0xf bank_mask:0x3
	v_mov_b32_dpp v243, v247 row_shl:8 row_mask:0xf bank_mask:0x3
	v_mov_b32_dpp v244, v248 row_shl:8 row_mask:0xf bank_mask:0x3
	v_mov_b32_dpp v245, v249 row_shl:8 row_mask:0xf bank_mask:0x3
	global_store_dwordx4 v[236:237], v[242:245], off
	s_and_b64 vcc, exec, s[0:1]
	s_cbranch_vccz .LBB0_919
	s_waitcnt vmcnt(0)
	v_readlane_b32 s40, v251, 54
	s_cmpk_gt_u32 s7, 0xff
	v_readlane_b32 s41, v251, 55
	s_cbranch_scc1 .LBB0_926
	s_barrier
